# k-inner MFMA order (same accumulator back to back) in 5 GEMM main loops, on top of saddr staging
# speedup vs baseline: 1.0118x; 1.0085x over previous
; #define PG8_STAGE(bufoff, gbase, voff) do { _Pragma("unroll") for (int _i = 0; _i < 2; ++_i) \
;         __builtin_amdgcn_global_load_lds((const unsigned*)((const char*)(gbase) + (voff)[_i]), (PG8_LAS unsigned*)(lds + (bufoff) + ldsw + _i * 8192), 16, 0, 0); } while (0)
; #define PG8_LDA(dst, b, h) do { _Pragma("unroll") for (int m = 0; m < 4; ++m) _Pragma("unroll") for (int k = 0; k < 2; ++k) dst[m][k] = *(const PG8_LAS bf16x8*)(lds + PG8_SA(b, h) + aoff + m * 2048 + k * 1024); } while (0)
; #define PG8_LDB(dst, b, h) do { _Pragma("unroll") for (int n = 0; n < 2; ++n) _Pragma("unroll") for (int k = 0; k < 2; ++k) dst[n][k] = *(const PG8_LAS bf16x8*)(lds + PG8_SB(b, h) + boff + n * 2048 + k * 1024); } while (0)
; #define PG8_MMA(ai, bj, At, Bt) do { __builtin_amdgcn_s_setprio(1); _Pragma("unroll") for (int m = 0; m < 4; ++m) _Pragma("unroll") for (int n = 0; n < 2; ++n) _Pragma("unroll") for (int k = 0; k < 2; ++k) \
;         acc[ai][bj][m][n] = __builtin_amdgcn_mfma_f32_16x16x32_bf16(Bt[n][k], At[m][k], acc[ai][bj][m][n], 0, 0, 0); __builtin_amdgcn_s_setprio(0); } while (0)
; #define PG8_WAIT_V(n) asm volatile("s_waitcnt vmcnt(" #n ")" ::: "memory")
; #define PG8_WAIT_L(n) asm volatile("s_waitcnt lgkmcnt(" #n ")" ::: "memory")
; #define PG8_BAR __builtin_amdgcn_s_barrier()
; #define PG8_SCHED __builtin_amdgcn_sched_barrier(0)
; template <class Epi, class Sched, bool ALIGN_EPI = false, bool SP2 = false>
; __device__ __forceinline__ void gemm_phase(PG8_LAS unsigned char* lds, const Gemm g, const Sched& S, const Epi& E) {
;     ...
;             PG8_LDB(B0, 0, 0); PG8_LDB(B1, 0, 1); PG8_SCHED; PG8_LDA(At, 0, 0); PG8_STAGE(PG8_SA(1, 1), a1 + hstep, voffA);
;             PG8_WAIT_V(8); PG8_WAIT_L(0); PG8_BAR; PG8_MMA(0, 0, At, B0); PG8_MMA(0, 1, At, B1); PG8_BAR; PG8_SCHED;
;             PG8_LDA(At, 0, 1); PG8_STAGE(PG8_SB(0, 0), b2, voffB); PG8_STAGE(PG8_SB(0, 1), b2 + hstep, voffB); PG8_STAGE(PG8_SA(0, 0), a2, voffA);
.LBB0_373:
	s_add_u32 s28, s26, 0xfff80080
	s_addc_u32 s29, s27, -1
	s_add_i32 s33, 0, 0x10000
	s_cmp_eq_u32 s55, 28
	s_cselect_b32 s31, s5, s29
	s_cselect_b32 s30, s11, s28
	v_add_u32_e32 v161, s33, v155
	s_cselect_b32 s29, s19, s54
	s_cselect_b32 s28, s21, s53
	s_add_i32 s58, 0, 0x14000
	ds_read_b128 v[142:145], v161
	ds_read_b128 v[146:149], v161 offset:1024
	ds_read_b128 v[150:153], v161 offset:2048
	ds_read_b128 v[162:165], v161 offset:3072
	v_add_u32_e32 v161, s58, v155
	ds_read_b128 v[166:169], v161
	ds_read_b128 v[170:173], v161 offset:1024
	ds_read_b128 v[174:177], v161 offset:2048
	ds_read_b128 v[178:181], v161 offset:3072
	v_lshl_add_u64 v[202:203], s[26:27], 0, v[140:141]
	s_add_i32 m0, s41, 0xc000
	ds_read_b128 v[182:185], v160
	ds_read_b128 v[186:189], v160 offset:1024
	ds_read_b128 v[190:193], v160 offset:2048
	ds_read_b128 v[194:197], v160 offset:3072
	ds_read_b128 v[198:201], v160 offset:4096
	ds_read_b128 v[206:209], v160 offset:5120
	ds_read_b128 v[210:213], v160 offset:6144
	ds_read_b128 v[214:217], v160 offset:7168
	global_load_lds_dwordx4 v140, s[26:27]
	v_lshl_add_u64 v[202:203], s[26:27], 0, v[138:139]
	s_add_i32 m0, s41, 0xe000
	s_nop 0
	global_load_lds_dwordx4 v138, s[26:27]
	s_waitcnt vmcnt(8)
	s_waitcnt lgkmcnt(0)
	s_barrier
	s_setprio 1
	s_waitcnt lgkmcnt(0)
	v_mfma_f32_16x16x32_bf16 v[130:133], v[142:145], v[182:185], v[130:133]
	v_mfma_f32_16x16x32_bf16 v[130:133], v[146:149], v[186:189], v[130:133]
	v_mfma_f32_16x16x32_bf16 v[126:129], v[150:153], v[182:185], v[126:129]
	v_mfma_f32_16x16x32_bf16 v[126:129], v[162:165], v[186:189], v[126:129]
	v_mfma_f32_16x16x32_bf16 v[114:117], v[142:145], v[190:193], v[114:117]
	v_mfma_f32_16x16x32_bf16 v[114:117], v[146:149], v[194:197], v[114:117]
	v_mfma_f32_16x16x32_bf16 v[110:113], v[150:153], v[190:193], v[110:113]
	v_mfma_f32_16x16x32_bf16 v[110:113], v[162:165], v[194:197], v[110:113]
	v_mfma_f32_16x16x32_bf16 v[98:101], v[142:145], v[198:201], v[98:101]
	v_mfma_f32_16x16x32_bf16 v[98:101], v[146:149], v[206:209], v[98:101]
	v_mfma_f32_16x16x32_bf16 v[94:97], v[150:153], v[198:201], v[94:97]
	v_mfma_f32_16x16x32_bf16 v[94:97], v[162:165], v[206:209], v[94:97]
	v_mfma_f32_16x16x32_bf16 v[82:85], v[142:145], v[210:213], v[82:85]
	v_mfma_f32_16x16x32_bf16 v[82:85], v[146:149], v[214:217], v[82:85]
	v_mfma_f32_16x16x32_bf16 v[78:81], v[150:153], v[210:213], v[78:81]
	v_mfma_f32_16x16x32_bf16 v[78:81], v[162:165], v[214:217], v[78:81]
	s_setprio 0
	s_setprio 1
	v_mfma_f32_16x16x32_bf16 v[122:125], v[166:169], v[182:185], v[122:125]
	v_mfma_f32_16x16x32_bf16 v[122:125], v[170:173], v[186:189], v[122:125]
	v_mfma_f32_16x16x32_bf16 v[118:121], v[174:177], v[182:185], v[118:121]
	v_mfma_f32_16x16x32_bf16 v[118:121], v[178:181], v[186:189], v[118:121]
	v_mfma_f32_16x16x32_bf16 v[106:109], v[166:169], v[190:193], v[106:109]
	v_mfma_f32_16x16x32_bf16 v[106:109], v[170:173], v[194:197], v[106:109]
	v_mfma_f32_16x16x32_bf16 v[102:105], v[174:177], v[190:193], v[102:105]
	v_mfma_f32_16x16x32_bf16 v[102:105], v[178:181], v[194:197], v[102:105]
	v_mfma_f32_16x16x32_bf16 v[90:93], v[166:169], v[198:201], v[90:93]
	v_mfma_f32_16x16x32_bf16 v[90:93], v[170:173], v[206:209], v[90:93]
	v_mfma_f32_16x16x32_bf16 v[86:89], v[174:177], v[198:201], v[86:89]
	v_mfma_f32_16x16x32_bf16 v[86:89], v[178:181], v[206:209], v[86:89]
	v_mfma_f32_16x16x32_bf16 v[74:77], v[166:169], v[210:213], v[74:77]
	v_mfma_f32_16x16x32_bf16 v[74:77], v[170:173], v[214:217], v[74:77]
	v_mfma_f32_16x16x32_bf16 v[70:73], v[174:177], v[210:213], v[70:73]
	v_mfma_f32_16x16x32_bf16 v[70:73], v[178:181], v[214:217], v[70:73]
	s_setprio 0
	s_barrier
	s_add_i32 s33, s33, s39
	v_lshl_add_u64 v[202:203], s[28:29], 0, v[0:1]
	s_mov_b32 m0, s33
	ds_read_b128 v[182:185], v160 offset:16384
	ds_read_b128 v[186:189], v160 offset:17408
	ds_read_b128 v[190:193], v160 offset:18432
	ds_read_b128 v[194:197], v160 offset:19456
	ds_read_b128 v[198:201], v160 offset:20480
	ds_read_b128 v[206:209], v160 offset:21504
	ds_read_b128 v[210:213], v160 offset:22528
	ds_read_b128 v[214:217], v160 offset:23552
	global_load_lds_dwordx4 v0, s[28:29]
	s_add_i32 m0, s33, 0x2000
	s_add_u32 s56, s28, 0x80000
	v_lshl_add_u64 v[218:219], s[28:29], 0, v[14:15]
	s_addc_u32 s57, s29, 0
	s_add_i32 s33, s58, s39
	global_load_lds_dwordx4 v14, s[28:29]
	v_lshl_add_u64 v[220:221], s[56:57], 0, v[0:1]
	s_mov_b32 m0, s33
	v_lshl_add_u64 v[222:223], s[30:31], 0, v[134:135]
	global_load_lds_dwordx4 v0, s[56:57]
	v_lshl_add_u64 v[220:221], s[56:57], 0, v[14:15]
	s_add_i32 m0, s33, 0x2000
	s_nop 0
	global_load_lds_dwordx4 v14, s[56:57]
	v_lshl_add_u64 v[220:221], s[30:31], 0, v[136:137]
	s_mov_b32 m0, s41
	s_nop 0
	global_load_lds_dwordx4 v136, s[30:31]
	s_mov_b32 m0, s42
	s_nop 0
	global_load_lds_dwordx4 v134, s[30:31]
	s_waitcnt vmcnt(8)
	s_waitcnt lgkmcnt(0)
	s_barrier
; #define PG8_STAGE(bufoff, gbase, voff) do { _Pragma("unroll") for (int _i = 0; _i < 2; ++_i) \
;         __builtin_amdgcn_global_load_lds((const unsigned*)((const char*)(gbase) + (voff)[_i]), (PG8_LAS unsigned*)(lds + (bufoff) + ldsw + _i * 8192), 16, 0, 0); } while (0)
; #define PG8_LDA(dst, b, h) do { _Pragma("unroll") for (int m = 0; m < 4; ++m) _Pragma("unroll") for (int k = 0; k < 2; ++k) dst[m][k] = *(const PG8_LAS bf16x8*)(lds + PG8_SA(b, h) + aoff + m * 2048 + k * 1024); } while (0)
; #define PG8_LDB(dst, b, h) do { _Pragma("unroll") for (int n = 0; n < 2; ++n) _Pragma("unroll") for (int k = 0; k < 2; ++k) dst[n][k] = *(const PG8_LAS bf16x8*)(lds + PG8_SB(b, h) + boff + n * 2048 + k * 1024); } while (0)
; #define PG8_MMA(ai, bj, At, Bt) do { __builtin_amdgcn_s_setprio(1); _Pragma("unroll") for (int m = 0; m < 4; ++m) _Pragma("unroll") for (int n = 0; n < 2; ++n) _Pragma("unroll") for (int k = 0; k < 2; ++k) \
;         acc[ai][bj][m][n] = __builtin_amdgcn_mfma_f32_16x16x32_bf16(Bt[n][k], At[m][k], acc[ai][bj][m][n], 0, 0, 0); __builtin_amdgcn_s_setprio(0); } while (0)
; #define PG8_WAIT_V(n) asm volatile("s_waitcnt vmcnt(" #n ")" ::: "memory")
; #define PG8_WAIT_L(n) asm volatile("s_waitcnt lgkmcnt(" #n ")" ::: "memory")
; #define PG8_BAR __builtin_amdgcn_s_barrier()
; #define PG8_SCHED __builtin_amdgcn_sched_barrier(0)
; template <class Epi, class Sched, bool ALIGN_EPI = false, bool SP2 = false>
; __device__ __forceinline__ void gemm_phase(PG8_LAS unsigned char* lds, const Gemm g, const Sched& S, const Epi& E) {
;     ...
;             PG8_WAIT_V(8); PG8_WAIT_L(0); PG8_BAR; PG8_MMA(1, 0, At, B0); PG8_MMA(1, 1, At, B1); PG8_BAR; PG8_SCHED;
;             PG8_LDB(B0, 1, 0); PG8_LDB(B1, 1, 1); PG8_SCHED; PG8_LDA(At, 1, 0); PG8_STAGE(PG8_SA(0, 1), a2 + hstep, voffA);
;             PG8_WAIT_V(8); PG8_WAIT_L(0); PG8_BAR; PG8_MMA(0, 0, At, B0); PG8_MMA(0, 1, At, B1); PG8_BAR; PG8_SCHED;
	s_setprio 1
	s_waitcnt lgkmcnt(0)
	v_mfma_f32_16x16x32_bf16 v[66:69], v[142:145], v[182:185], v[66:69]
	v_mfma_f32_16x16x32_bf16 v[66:69], v[146:149], v[186:189], v[66:69]
	v_mfma_f32_16x16x32_bf16 v[62:65], v[150:153], v[182:185], v[62:65]
	v_mfma_f32_16x16x32_bf16 v[62:65], v[162:165], v[186:189], v[62:65]
	v_mfma_f32_16x16x32_bf16 v[50:53], v[142:145], v[190:193], v[50:53]
	v_mfma_f32_16x16x32_bf16 v[50:53], v[146:149], v[194:197], v[50:53]
	v_mfma_f32_16x16x32_bf16 v[46:49], v[150:153], v[190:193], v[46:49]
	v_mfma_f32_16x16x32_bf16 v[46:49], v[162:165], v[194:197], v[46:49]
	v_mfma_f32_16x16x32_bf16 v[34:37], v[142:145], v[198:201], v[34:37]
	v_mfma_f32_16x16x32_bf16 v[34:37], v[146:149], v[206:209], v[34:37]
	v_mfma_f32_16x16x32_bf16 v[30:33], v[150:153], v[198:201], v[30:33]
	v_mfma_f32_16x16x32_bf16 v[30:33], v[162:165], v[206:209], v[30:33]
	v_mfma_f32_16x16x32_bf16 v[18:21], v[142:145], v[210:213], v[18:21]
	v_mfma_f32_16x16x32_bf16 v[18:21], v[146:149], v[214:217], v[18:21]
	v_mfma_f32_16x16x32_bf16 v[10:13], v[150:153], v[210:213], v[10:13]
	v_mfma_f32_16x16x32_bf16 v[10:13], v[162:165], v[214:217], v[10:13]
	s_setprio 0
	s_setprio 1
	v_mfma_f32_16x16x32_bf16 v[58:61], v[166:169], v[182:185], v[58:61]
	v_mfma_f32_16x16x32_bf16 v[58:61], v[170:173], v[186:189], v[58:61]
	v_mfma_f32_16x16x32_bf16 v[54:57], v[174:177], v[182:185], v[54:57]
	v_mfma_f32_16x16x32_bf16 v[54:57], v[178:181], v[186:189], v[54:57]
	v_mfma_f32_16x16x32_bf16 v[42:45], v[166:169], v[190:193], v[42:45]
	v_mfma_f32_16x16x32_bf16 v[42:45], v[170:173], v[194:197], v[42:45]
	v_mfma_f32_16x16x32_bf16 v[38:41], v[174:177], v[190:193], v[38:41]
	v_mfma_f32_16x16x32_bf16 v[38:41], v[178:181], v[194:197], v[38:41]
	v_mfma_f32_16x16x32_bf16 v[26:29], v[166:169], v[198:201], v[26:29]
	v_mfma_f32_16x16x32_bf16 v[26:29], v[170:173], v[206:209], v[26:29]
	v_mfma_f32_16x16x32_bf16 v[22:25], v[174:177], v[198:201], v[22:25]
	v_mfma_f32_16x16x32_bf16 v[22:25], v[178:181], v[206:209], v[22:25]
	v_mfma_f32_16x16x32_bf16 v[6:9], v[166:169], v[210:213], v[6:9]
	v_mfma_f32_16x16x32_bf16 v[6:9], v[170:173], v[214:217], v[6:9]
	v_mfma_f32_16x16x32_bf16 v[2:5], v[174:177], v[210:213], v[2:5]
	v_mfma_f32_16x16x32_bf16 v[2:5], v[178:181], v[214:217], v[2:5]
	s_setprio 0
	s_barrier
	s_add_i32 s33, 0, 0x18000
	v_add_u32_e32 v161, s33, v155
	s_add_i32 s56, 0, 0x1c000
	ds_read_b128 v[142:145], v161
	ds_read_b128 v[146:149], v161 offset:1024
	ds_read_b128 v[150:153], v161 offset:2048
	ds_read_b128 v[162:165], v161 offset:3072
	v_add_u32_e32 v161, s56, v155
	ds_read_b128 v[166:169], v161
	ds_read_b128 v[170:173], v161 offset:1024
	ds_read_b128 v[174:177], v161 offset:2048
	ds_read_b128 v[178:181], v161 offset:3072
	s_add_u32 s30, s30, 0x80000
	s_addc_u32 s31, s31, 0
	s_mov_b32 m0, s43
	v_lshl_add_u64 v[224:225], s[30:31], 0, v[136:137]
	ds_read_b128 v[182:185], v160 offset:32768
	ds_read_b128 v[186:189], v160 offset:33792
	ds_read_b128 v[190:193], v160 offset:34816
	ds_read_b128 v[194:197], v160 offset:35840
	ds_read_b128 v[198:201], v160 offset:36864
	ds_read_b128 v[206:209], v160 offset:37888
	ds_read_b128 v[210:213], v160 offset:38912
	ds_read_b128 v[214:217], v160 offset:39936
	global_load_lds_dwordx4 v136, s[30:31]
	v_lshl_add_u64 v[224:225], s[30:31], 0, v[134:135]
	s_mov_b32 m0, s44
	s_nop 0
	global_load_lds_dwordx4 v134, s[30:31]
	s_waitcnt vmcnt(8)
	s_waitcnt lgkmcnt(0)
	s_barrier
	s_setprio 1
	s_waitcnt lgkmcnt(0)
	v_mfma_f32_16x16x32_bf16 v[130:133], v[142:145], v[182:185], v[130:133]
	v_mfma_f32_16x16x32_bf16 v[130:133], v[146:149], v[186:189], v[130:133]
	v_mfma_f32_16x16x32_bf16 v[126:129], v[150:153], v[182:185], v[126:129]
	v_mfma_f32_16x16x32_bf16 v[126:129], v[162:165], v[186:189], v[126:129]
	v_mfma_f32_16x16x32_bf16 v[114:117], v[142:145], v[190:193], v[114:117]
	v_mfma_f32_16x16x32_bf16 v[114:117], v[146:149], v[194:197], v[114:117]
	v_mfma_f32_16x16x32_bf16 v[110:113], v[150:153], v[190:193], v[110:113]
	v_mfma_f32_16x16x32_bf16 v[110:113], v[162:165], v[194:197], v[110:113]
	v_mfma_f32_16x16x32_bf16 v[98:101], v[142:145], v[198:201], v[98:101]
	v_mfma_f32_16x16x32_bf16 v[98:101], v[146:149], v[206:209], v[98:101]
	v_mfma_f32_16x16x32_bf16 v[94:97], v[150:153], v[198:201], v[94:97]
	v_mfma_f32_16x16x32_bf16 v[94:97], v[162:165], v[206:209], v[94:97]
	v_mfma_f32_16x16x32_bf16 v[82:85], v[142:145], v[210:213], v[82:85]
	v_mfma_f32_16x16x32_bf16 v[82:85], v[146:149], v[214:217], v[82:85]
	v_mfma_f32_16x16x32_bf16 v[78:81], v[150:153], v[210:213], v[78:81]
	v_mfma_f32_16x16x32_bf16 v[78:81], v[162:165], v[214:217], v[78:81]
	s_setprio 0
	s_setprio 1
	v_mfma_f32_16x16x32_bf16 v[122:125], v[166:169], v[182:185], v[122:125]
	v_mfma_f32_16x16x32_bf16 v[122:125], v[170:173], v[186:189], v[122:125]
	v_mfma_f32_16x16x32_bf16 v[118:121], v[174:177], v[182:185], v[118:121]
	v_mfma_f32_16x16x32_bf16 v[118:121], v[178:181], v[186:189], v[118:121]
	v_mfma_f32_16x16x32_bf16 v[106:109], v[166:169], v[190:193], v[106:109]
	v_mfma_f32_16x16x32_bf16 v[106:109], v[170:173], v[194:197], v[106:109]
	v_mfma_f32_16x16x32_bf16 v[102:105], v[174:177], v[190:193], v[102:105]
	v_mfma_f32_16x16x32_bf16 v[102:105], v[178:181], v[194:197], v[102:105]
	v_mfma_f32_16x16x32_bf16 v[90:93], v[166:169], v[198:201], v[90:93]
	v_mfma_f32_16x16x32_bf16 v[90:93], v[170:173], v[206:209], v[90:93]
	v_mfma_f32_16x16x32_bf16 v[86:89], v[174:177], v[198:201], v[86:89]
	v_mfma_f32_16x16x32_bf16 v[86:89], v[178:181], v[206:209], v[86:89]
	v_mfma_f32_16x16x32_bf16 v[74:77], v[166:169], v[210:213], v[74:77]
	v_mfma_f32_16x16x32_bf16 v[74:77], v[170:173], v[214:217], v[74:77]
	v_mfma_f32_16x16x32_bf16 v[70:73], v[174:177], v[210:213], v[70:73]
	v_mfma_f32_16x16x32_bf16 v[70:73], v[178:181], v[214:217], v[70:73]
	s_setprio 0
	s_barrier
; #define PG8_STAGE(bufoff, gbase, voff) do { _Pragma("unroll") for (int _i = 0; _i < 2; ++_i) \
;         __builtin_amdgcn_global_load_lds((const unsigned*)((const char*)(gbase) + (voff)[_i]), (PG8_LAS unsigned*)(lds + (bufoff) + ldsw + _i * 8192), 16, 0, 0); } while (0)
; #define PG8_LDA(dst, b, h) do { _Pragma("unroll") for (int m = 0; m < 4; ++m) _Pragma("unroll") for (int k = 0; k < 2; ++k) dst[m][k] = *(const PG8_LAS bf16x8*)(lds + PG8_SA(b, h) + aoff + m * 2048 + k * 1024); } while (0)
; #define PG8_MMA(ai, bj, At, Bt) do { __builtin_amdgcn_s_setprio(1); _Pragma("unroll") for (int m = 0; m < 4; ++m) _Pragma("unroll") for (int n = 0; n < 2; ++n) _Pragma("unroll") for (int k = 0; k < 2; ++k) \
;         acc[ai][bj][m][n] = __builtin_amdgcn_mfma_f32_16x16x32_bf16(Bt[n][k], At[m][k], acc[ai][bj][m][n], 0, 0, 0); __builtin_amdgcn_s_setprio(0); } while (0)
; #define PG8_WAIT_V(n) asm volatile("s_waitcnt vmcnt(" #n ")" ::: "memory")
; #define PG8_WAIT_L(n) asm volatile("s_waitcnt lgkmcnt(" #n ")" ::: "memory")
; #define PG8_BAR __builtin_amdgcn_s_barrier()
; #define PG8_SCHED __builtin_amdgcn_sched_barrier(0)
; template <class Epi, class Sched, bool ALIGN_EPI = false, bool SP2 = false>
; __device__ __forceinline__ void gemm_phase(PG8_LAS unsigned char* lds, const Gemm g, const Sched& S, const Epi& E) {
;     ...
;             PG8_LDA(At, 1, 1); PG8_STAGE(PG8_SB(1, 0), b3, voffB); PG8_STAGE(PG8_SB(1, 1), b3 + hstep, voffB); PG8_STAGE(PG8_SA(1, 0), a3, voffA);
;             PG8_WAIT_V(8); PG8_WAIT_L(0); PG8_BAR; PG8_MMA(1, 0, At, B0); PG8_MMA(1, 1, At, B1); PG8_BAR; PG8_SCHED;
	s_add_i32 s30, s33, s39
	v_lshl_add_u64 v[202:203], v[202:203], 0, s[92:93]
	s_mov_b32 m0, s30
	ds_read_b128 v[182:185], v160 offset:49152
	ds_read_b128 v[186:189], v160 offset:50176
	ds_read_b128 v[190:193], v160 offset:51200
	ds_read_b128 v[194:197], v160 offset:52224
	ds_read_b128 v[198:201], v160 offset:53248
	ds_read_b128 v[206:209], v160 offset:54272
	ds_read_b128 v[210:213], v160 offset:55296
	ds_read_b128 v[214:217], v160 offset:56320
	global_load_lds_dwordx4 v[202:203], off
	s_add_i32 m0, s30, 0x2000
	s_add_u32 s28, s28, 0x80080
	v_lshl_add_u64 v[202:203], v[218:219], 0, s[92:93]
	s_addc_u32 s29, s29, 0
	s_add_i32 s30, s56, s39
	global_load_lds_dwordx4 v[202:203], off
	v_lshl_add_u64 v[202:203], s[28:29], 0, v[0:1]
	s_mov_b32 m0, s30
	s_nop 0
	global_load_lds_dwordx4 v0, s[28:29]
	v_lshl_add_u64 v[202:203], s[28:29], 0, v[14:15]
	s_add_i32 m0, s30, 0x2000
	s_nop 0
	global_load_lds_dwordx4 v14, s[28:29]
	v_lshl_add_u64 v[202:203], v[220:221], 0, s[92:93]
	s_mov_b32 m0, s46
	s_nop 0
	global_load_lds_dwordx4 v[202:203], off
	v_lshl_add_u64 v[202:203], v[222:223], 0, s[92:93]
	s_mov_b32 m0, s47
	s_nop 0
	global_load_lds_dwordx4 v[202:203], off
	s_waitcnt vmcnt(8)
	s_waitcnt lgkmcnt(0)
	s_barrier
	s_setprio 1
	s_waitcnt lgkmcnt(0)
	v_mfma_f32_16x16x32_bf16 v[66:69], v[142:145], v[182:185], v[66:69]
	v_mfma_f32_16x16x32_bf16 v[66:69], v[146:149], v[186:189], v[66:69]
	v_mfma_f32_16x16x32_bf16 v[62:65], v[150:153], v[182:185], v[62:65]
	v_mfma_f32_16x16x32_bf16 v[62:65], v[162:165], v[186:189], v[62:65]
	v_mfma_f32_16x16x32_bf16 v[50:53], v[142:145], v[190:193], v[50:53]
	v_mfma_f32_16x16x32_bf16 v[50:53], v[146:149], v[194:197], v[50:53]
	v_mfma_f32_16x16x32_bf16 v[46:49], v[150:153], v[190:193], v[46:49]
	v_mfma_f32_16x16x32_bf16 v[46:49], v[162:165], v[194:197], v[46:49]
	v_mfma_f32_16x16x32_bf16 v[34:37], v[142:145], v[198:201], v[34:37]
	v_mfma_f32_16x16x32_bf16 v[34:37], v[146:149], v[206:209], v[34:37]
	v_mfma_f32_16x16x32_bf16 v[30:33], v[150:153], v[198:201], v[30:33]
	v_mfma_f32_16x16x32_bf16 v[30:33], v[162:165], v[206:209], v[30:33]
	v_mfma_f32_16x16x32_bf16 v[18:21], v[142:145], v[210:213], v[18:21]
	v_mfma_f32_16x16x32_bf16 v[18:21], v[146:149], v[214:217], v[18:21]
	v_mfma_f32_16x16x32_bf16 v[10:13], v[150:153], v[210:213], v[10:13]
	v_mfma_f32_16x16x32_bf16 v[10:13], v[162:165], v[214:217], v[10:13]
	s_setprio 0
	s_setprio 1
	v_mfma_f32_16x16x32_bf16 v[58:61], v[166:169], v[182:185], v[58:61]
	v_mfma_f32_16x16x32_bf16 v[58:61], v[170:173], v[186:189], v[58:61]
	v_mfma_f32_16x16x32_bf16 v[54:57], v[174:177], v[182:185], v[54:57]
	v_mfma_f32_16x16x32_bf16 v[54:57], v[178:181], v[186:189], v[54:57]
	v_mfma_f32_16x16x32_bf16 v[42:45], v[166:169], v[190:193], v[42:45]
	v_mfma_f32_16x16x32_bf16 v[42:45], v[170:173], v[194:197], v[42:45]
	v_mfma_f32_16x16x32_bf16 v[38:41], v[174:177], v[190:193], v[38:41]
	v_mfma_f32_16x16x32_bf16 v[38:41], v[178:181], v[194:197], v[38:41]
	v_mfma_f32_16x16x32_bf16 v[26:29], v[166:169], v[198:201], v[26:29]
	v_mfma_f32_16x16x32_bf16 v[26:29], v[170:173], v[206:209], v[26:29]
	v_mfma_f32_16x16x32_bf16 v[22:25], v[174:177], v[198:201], v[22:25]
	v_mfma_f32_16x16x32_bf16 v[22:25], v[178:181], v[206:209], v[22:25]
	v_mfma_f32_16x16x32_bf16 v[6:9], v[166:169], v[210:213], v[6:9]
	v_mfma_f32_16x16x32_bf16 v[6:9], v[170:173], v[214:217], v[6:9]
	v_mfma_f32_16x16x32_bf16 v[2:5], v[174:177], v[210:213], v[2:5]
	v_mfma_f32_16x16x32_bf16 v[2:5], v[178:181], v[214:217], v[2:5]
	s_setprio 0
	s_barrier
	s_add_i32 s55, s55, 2
	s_add_u32 s53, s53, 0x100
	s_addc_u32 s54, s54, 0
	s_add_u32 s26, s26, 0x100
	s_addc_u32 s27, s27, 0
	s_cmp_gt_u32 s55, 29
	s_cbranch_scc0 .LBB0_373
	s_and_b64 vcc, exec, s[14:15]
	s_cbranch_vccz .LBB0_376
	s_barrier

; #define PG8_STAGE(bufoff, gbase, voff) do { _Pragma("unroll") for (int _i = 0; _i < 2; ++_i) \
;         __builtin_amdgcn_global_load_lds((const unsigned*)((const char*)(gbase) + (voff)[_i]), (PG8_LAS unsigned*)(lds + (bufoff) + ldsw + _i * 8192), 16, 0, 0); } while (0)
; #define PG8_LDA(dst, b, h) do { _Pragma("unroll") for (int m = 0; m < 4; ++m) _Pragma("unroll") for (int k = 0; k < 2; ++k) dst[m][k] = *(const PG8_LAS bf16x8*)(lds + PG8_SA(b, h) + aoff + m * 2048 + k * 1024); } while (0)
; #define PG8_LDB(dst, b, h) do { _Pragma("unroll") for (int n = 0; n < 2; ++n) _Pragma("unroll") for (int k = 0; k < 2; ++k) dst[n][k] = *(const PG8_LAS bf16x8*)(lds + PG8_SB(b, h) + boff + n * 2048 + k * 1024); } while (0)
; #define PG8_MMA(ai, bj, At, Bt) do { __builtin_amdgcn_s_setprio(1); _Pragma("unroll") for (int m = 0; m < 4; ++m) _Pragma("unroll") for (int n = 0; n < 2; ++n) _Pragma("unroll") for (int k = 0; k < 2; ++k) \
;         acc[ai][bj][m][n] = __builtin_amdgcn_mfma_f32_16x16x32_bf16(Bt[n][k], At[m][k], acc[ai][bj][m][n], 0, 0, 0); __builtin_amdgcn_s_setprio(0); } while (0)
; #define PG8_WAIT_V(n) asm volatile("s_waitcnt vmcnt(" #n ")" ::: "memory")
; #define PG8_WAIT_L(n) asm volatile("s_waitcnt lgkmcnt(" #n ")" ::: "memory")
; #define PG8_BAR __builtin_amdgcn_s_barrier()
; #define PG8_SCHED __builtin_amdgcn_sched_barrier(0)
; template <class Epi, class Sched, bool ALIGN_EPI = false, bool SP2 = false>
; __device__ __forceinline__ void gemm_phase(PG8_LAS unsigned char* lds, const Gemm g, const Sched& S, const Epi& E) {
;     ...
;             PG8_LDB(B0, 0, 0); PG8_LDB(B1, 0, 1); PG8_SCHED; PG8_LDA(At, 0, 0); PG8_STAGE(PG8_SA(1, 1), a1 + hstep, voffA);
;             PG8_WAIT_V(8); PG8_WAIT_L(0); PG8_BAR; PG8_MMA(0, 0, At, B0); PG8_MMA(0, 1, At, B1); PG8_BAR; PG8_SCHED;
;             PG8_LDA(At, 0, 1); PG8_STAGE(PG8_SB(0, 0), b2, voffB); PG8_STAGE(PG8_SB(0, 1), b2 + hstep, voffB); PG8_STAGE(PG8_SA(0, 0), a2, voffA);
.LBB0_482:
	s_add_u32 s22, s20, 0x100
	s_addc_u32 s23, s21, 0
	s_add_i32 s33, 0, 0x10000
	s_cmpk_eq_i32 s52, 0x54
	s_cselect_b32 s27, s5, s23
	s_cselect_b32 s26, s4, s22
	s_cselect_b32 s25, s19, s51
	s_cselect_b32 s24, s18, s50
	s_add_i32 s53, 0, 0x14000
	v_add_u32_e32 v138, s33, v199
	v_add_u32_e32 v162, s53, v199
	ds_read_b128 v[118:121], v138
	ds_read_b128 v[130:133], v138 offset:1024
	ds_read_b128 v[134:137], v138 offset:2048
	ds_read_b128 v[138:141], v138 offset:3072
	ds_read_b128 v[146:149], v162
	ds_read_b128 v[154:157], v162 offset:1024
	ds_read_b128 v[158:161], v162 offset:2048
	ds_read_b128 v[162:165], v162 offset:3072
	v_lshl_add_u64 v[202:203], s[20:21], 0, v[212:213]
	s_add_i32 m0, s37, 0xc000
	ds_read_b128 v[166:169], v201
	ds_read_b128 v[170:173], v201 offset:1024
	ds_read_b128 v[174:177], v201 offset:2048
	ds_read_b128 v[178:181], v201 offset:3072
	ds_read_b128 v[182:185], v201 offset:4096
	ds_read_b128 v[186:189], v201 offset:5120
	ds_read_b128 v[190:193], v201 offset:6144
	ds_read_b128 v[194:197], v201 offset:7168
	global_load_lds_dwordx4 v212, s[20:21]
	v_lshl_add_u64 v[202:203], s[20:21], 0, v[210:211]
	s_add_i32 m0, s37, 0xe000
	s_nop 0
	global_load_lds_dwordx4 v210, s[20:21]
	s_waitcnt vmcnt(8)
	s_waitcnt lgkmcnt(0)
	s_barrier
	s_setprio 1
	s_waitcnt lgkmcnt(0)
	v_mfma_f32_16x16x32_bf16 v[150:153], v[118:121], v[166:169], v[150:153]
	v_mfma_f32_16x16x32_bf16 v[150:153], v[130:133], v[170:173], v[150:153]
	v_mfma_f32_16x16x32_bf16 v[142:145], v[134:137], v[166:169], v[142:145]
	v_mfma_f32_16x16x32_bf16 v[142:145], v[138:141], v[170:173], v[142:145]
	v_mfma_f32_16x16x32_bf16 v[114:117], v[118:121], v[174:177], v[114:117]
	v_mfma_f32_16x16x32_bf16 v[114:117], v[130:133], v[178:181], v[114:117]
	v_mfma_f32_16x16x32_bf16 v[110:113], v[134:137], v[174:177], v[110:113]
	v_mfma_f32_16x16x32_bf16 v[110:113], v[138:141], v[178:181], v[110:113]
	v_mfma_f32_16x16x32_bf16 v[98:101], v[118:121], v[182:185], v[98:101]
	v_mfma_f32_16x16x32_bf16 v[98:101], v[130:133], v[186:189], v[98:101]
	v_mfma_f32_16x16x32_bf16 v[94:97], v[134:137], v[182:185], v[94:97]
	v_mfma_f32_16x16x32_bf16 v[94:97], v[138:141], v[186:189], v[94:97]
	v_mfma_f32_16x16x32_bf16 v[82:85], v[118:121], v[190:193], v[82:85]
	v_mfma_f32_16x16x32_bf16 v[82:85], v[130:133], v[194:197], v[82:85]
	v_mfma_f32_16x16x32_bf16 v[78:81], v[134:137], v[190:193], v[78:81]
	v_mfma_f32_16x16x32_bf16 v[78:81], v[138:141], v[194:197], v[78:81]
	s_setprio 0
	s_setprio 1
	v_mfma_f32_16x16x32_bf16 v[126:129], v[146:149], v[166:169], v[126:129]
	v_mfma_f32_16x16x32_bf16 v[126:129], v[154:157], v[170:173], v[126:129]
	v_mfma_f32_16x16x32_bf16 v[122:125], v[158:161], v[166:169], v[122:125]
	v_mfma_f32_16x16x32_bf16 v[122:125], v[162:165], v[170:173], v[122:125]
	v_mfma_f32_16x16x32_bf16 v[106:109], v[146:149], v[174:177], v[106:109]
	v_mfma_f32_16x16x32_bf16 v[106:109], v[154:157], v[178:181], v[106:109]
	v_mfma_f32_16x16x32_bf16 v[102:105], v[158:161], v[174:177], v[102:105]
	v_mfma_f32_16x16x32_bf16 v[102:105], v[162:165], v[178:181], v[102:105]
	v_mfma_f32_16x16x32_bf16 v[90:93], v[146:149], v[182:185], v[90:93]
	v_mfma_f32_16x16x32_bf16 v[90:93], v[154:157], v[186:189], v[90:93]
	v_mfma_f32_16x16x32_bf16 v[86:89], v[158:161], v[182:185], v[86:89]
	v_mfma_f32_16x16x32_bf16 v[86:89], v[162:165], v[186:189], v[86:89]
	v_mfma_f32_16x16x32_bf16 v[74:77], v[146:149], v[190:193], v[74:77]
	v_mfma_f32_16x16x32_bf16 v[74:77], v[154:157], v[194:197], v[74:77]
	v_mfma_f32_16x16x32_bf16 v[70:73], v[158:161], v[190:193], v[70:73]
	v_mfma_f32_16x16x32_bf16 v[70:73], v[162:165], v[194:197], v[70:73]
	s_setprio 0
	s_barrier
	s_add_i32 s20, s33, s36
	v_lshl_add_u64 v[202:203], s[24:25], 0, v[0:1]
	s_mov_b32 m0, s20
	ds_read_b128 v[166:169], v201 offset:16384
	ds_read_b128 v[170:173], v201 offset:17408
	ds_read_b128 v[174:177], v201 offset:18432
	ds_read_b128 v[178:181], v201 offset:19456
	ds_read_b128 v[182:185], v201 offset:20480
	ds_read_b128 v[186:189], v201 offset:21504
	ds_read_b128 v[190:193], v201 offset:22528
	ds_read_b128 v[194:197], v201 offset:23552
	global_load_lds_dwordx4 v0, s[24:25]
	s_add_i32 m0, s20, 0x2000
	s_add_u32 s20, s24, 0x160000
	v_lshl_add_u64 v[214:215], s[24:25], 0, v[208:209]
	s_addc_u32 s21, s25, 0
	s_add_i32 s33, s53, s36
	global_load_lds_dwordx4 v208, s[24:25]
	v_lshl_add_u64 v[216:217], s[20:21], 0, v[0:1]
	s_mov_b32 m0, s33
	v_lshl_add_u64 v[218:219], s[26:27], 0, v[206:207]
	global_load_lds_dwordx4 v0, s[20:21]
	v_lshl_add_u64 v[216:217], s[20:21], 0, v[208:209]
	s_add_i32 m0, s33, 0x2000
	s_nop 0
	global_load_lds_dwordx4 v208, s[20:21]
	v_lshl_add_u64 v[216:217], s[26:27], 0, v[14:15]
	s_mov_b32 m0, s37
	s_nop 0
	global_load_lds_dwordx4 v14, s[26:27]
	s_mov_b32 m0, s38
	s_nop 0
	global_load_lds_dwordx4 v206, s[26:27]
	s_waitcnt vmcnt(8)
	s_waitcnt lgkmcnt(0)
	s_barrier
; #define PG8_STAGE(bufoff, gbase, voff) do { _Pragma("unroll") for (int _i = 0; _i < 2; ++_i) \
;         __builtin_amdgcn_global_load_lds((const unsigned*)((const char*)(gbase) + (voff)[_i]), (PG8_LAS unsigned*)(lds + (bufoff) + ldsw + _i * 8192), 16, 0, 0); } while (0)
; #define PG8_LDA(dst, b, h) do { _Pragma("unroll") for (int m = 0; m < 4; ++m) _Pragma("unroll") for (int k = 0; k < 2; ++k) dst[m][k] = *(const PG8_LAS bf16x8*)(lds + PG8_SA(b, h) + aoff + m * 2048 + k * 1024); } while (0)
; #define PG8_LDB(dst, b, h) do { _Pragma("unroll") for (int n = 0; n < 2; ++n) _Pragma("unroll") for (int k = 0; k < 2; ++k) dst[n][k] = *(const PG8_LAS bf16x8*)(lds + PG8_SB(b, h) + boff + n * 2048 + k * 1024); } while (0)
; #define PG8_MMA(ai, bj, At, Bt) do { __builtin_amdgcn_s_setprio(1); _Pragma("unroll") for (int m = 0; m < 4; ++m) _Pragma("unroll") for (int n = 0; n < 2; ++n) _Pragma("unroll") for (int k = 0; k < 2; ++k) \
;         acc[ai][bj][m][n] = __builtin_amdgcn_mfma_f32_16x16x32_bf16(Bt[n][k], At[m][k], acc[ai][bj][m][n], 0, 0, 0); __builtin_amdgcn_s_setprio(0); } while (0)
; #define PG8_WAIT_V(n) asm volatile("s_waitcnt vmcnt(" #n ")" ::: "memory")
; #define PG8_WAIT_L(n) asm volatile("s_waitcnt lgkmcnt(" #n ")" ::: "memory")
; #define PG8_BAR __builtin_amdgcn_s_barrier()
; #define PG8_SCHED __builtin_amdgcn_sched_barrier(0)
; template <class Epi, class Sched, bool ALIGN_EPI = false, bool SP2 = false>
; __device__ __forceinline__ void gemm_phase(PG8_LAS unsigned char* lds, const Gemm g, const Sched& S, const Epi& E) {
;     ...
;             PG8_WAIT_V(8); PG8_WAIT_L(0); PG8_BAR; PG8_MMA(1, 0, At, B0); PG8_MMA(1, 1, At, B1); PG8_BAR; PG8_SCHED;
;             PG8_LDB(B0, 1, 0); PG8_LDB(B1, 1, 1); PG8_SCHED; PG8_LDA(At, 1, 0); PG8_STAGE(PG8_SA(0, 1), a2 + hstep, voffA);
;             PG8_WAIT_V(8); PG8_WAIT_L(0); PG8_BAR; PG8_MMA(0, 0, At, B0); PG8_MMA(0, 1, At, B1); PG8_BAR; PG8_SCHED;
	s_setprio 1
	s_waitcnt lgkmcnt(0)
	v_mfma_f32_16x16x32_bf16 v[66:69], v[118:121], v[166:169], v[66:69]
	v_mfma_f32_16x16x32_bf16 v[66:69], v[130:133], v[170:173], v[66:69]
	v_mfma_f32_16x16x32_bf16 v[62:65], v[134:137], v[166:169], v[62:65]
	v_mfma_f32_16x16x32_bf16 v[62:65], v[138:141], v[170:173], v[62:65]
	v_mfma_f32_16x16x32_bf16 v[50:53], v[118:121], v[174:177], v[50:53]
	v_mfma_f32_16x16x32_bf16 v[50:53], v[130:133], v[178:181], v[50:53]
	v_mfma_f32_16x16x32_bf16 v[46:49], v[134:137], v[174:177], v[46:49]
	v_mfma_f32_16x16x32_bf16 v[46:49], v[138:141], v[178:181], v[46:49]
	v_mfma_f32_16x16x32_bf16 v[34:37], v[118:121], v[182:185], v[34:37]
	v_mfma_f32_16x16x32_bf16 v[34:37], v[130:133], v[186:189], v[34:37]
	v_mfma_f32_16x16x32_bf16 v[30:33], v[134:137], v[182:185], v[30:33]
	v_mfma_f32_16x16x32_bf16 v[30:33], v[138:141], v[186:189], v[30:33]
	v_mfma_f32_16x16x32_bf16 v[18:21], v[118:121], v[190:193], v[18:21]
	v_mfma_f32_16x16x32_bf16 v[18:21], v[130:133], v[194:197], v[18:21]
	v_mfma_f32_16x16x32_bf16 v[10:13], v[134:137], v[190:193], v[10:13]
	v_mfma_f32_16x16x32_bf16 v[10:13], v[138:141], v[194:197], v[10:13]
	s_setprio 0
	s_setprio 1
	v_mfma_f32_16x16x32_bf16 v[58:61], v[146:149], v[166:169], v[58:61]
	v_mfma_f32_16x16x32_bf16 v[58:61], v[154:157], v[170:173], v[58:61]
	v_mfma_f32_16x16x32_bf16 v[54:57], v[158:161], v[166:169], v[54:57]
	v_mfma_f32_16x16x32_bf16 v[54:57], v[162:165], v[170:173], v[54:57]
	v_mfma_f32_16x16x32_bf16 v[42:45], v[146:149], v[174:177], v[42:45]
	v_mfma_f32_16x16x32_bf16 v[42:45], v[154:157], v[178:181], v[42:45]
	v_mfma_f32_16x16x32_bf16 v[38:41], v[158:161], v[174:177], v[38:41]
	v_mfma_f32_16x16x32_bf16 v[38:41], v[162:165], v[178:181], v[38:41]
	v_mfma_f32_16x16x32_bf16 v[26:29], v[146:149], v[182:185], v[26:29]
	v_mfma_f32_16x16x32_bf16 v[26:29], v[154:157], v[186:189], v[26:29]
	v_mfma_f32_16x16x32_bf16 v[22:25], v[158:161], v[182:185], v[22:25]
	v_mfma_f32_16x16x32_bf16 v[22:25], v[162:165], v[186:189], v[22:25]
	v_mfma_f32_16x16x32_bf16 v[6:9], v[146:149], v[190:193], v[6:9]
	v_mfma_f32_16x16x32_bf16 v[6:9], v[154:157], v[194:197], v[6:9]
	v_mfma_f32_16x16x32_bf16 v[2:5], v[158:161], v[190:193], v[2:5]
	v_mfma_f32_16x16x32_bf16 v[2:5], v[162:165], v[194:197], v[2:5]
	s_setprio 0
	s_barrier
	s_add_i32 s33, 0, 0x18000
	s_add_i32 s53, 0, 0x1c000
	v_add_u32_e32 v138, s33, v199
	v_add_u32_e32 v162, s53, v199
	ds_read_b128 v[118:121], v138
	ds_read_b128 v[130:133], v138 offset:1024
	ds_read_b128 v[134:137], v138 offset:2048
	ds_read_b128 v[138:141], v138 offset:3072
	ds_read_b128 v[146:149], v162
	ds_read_b128 v[154:157], v162 offset:1024
	ds_read_b128 v[158:161], v162 offset:2048
	ds_read_b128 v[162:165], v162 offset:3072
	s_add_u32 s20, s26, 0x160000
	s_addc_u32 s21, s27, 0
	s_mov_b32 m0, s39
	v_lshl_add_u64 v[220:221], s[20:21], 0, v[14:15]
	ds_read_b128 v[166:169], v201 offset:32768
	ds_read_b128 v[170:173], v201 offset:33792
	ds_read_b128 v[174:177], v201 offset:34816
	ds_read_b128 v[178:181], v201 offset:35840
	ds_read_b128 v[182:185], v201 offset:36864
	ds_read_b128 v[186:189], v201 offset:37888
	ds_read_b128 v[190:193], v201 offset:38912
	ds_read_b128 v[194:197], v201 offset:39936
	global_load_lds_dwordx4 v14, s[20:21]
	v_lshl_add_u64 v[220:221], s[20:21], 0, v[206:207]
	s_mov_b32 m0, s40
	s_nop 0
	global_load_lds_dwordx4 v206, s[20:21]
	s_waitcnt vmcnt(8)
	s_waitcnt lgkmcnt(0)
	s_barrier
	s_setprio 1
	s_waitcnt lgkmcnt(0)
	v_mfma_f32_16x16x32_bf16 v[150:153], v[118:121], v[166:169], v[150:153]
	v_mfma_f32_16x16x32_bf16 v[150:153], v[130:133], v[170:173], v[150:153]
	v_mfma_f32_16x16x32_bf16 v[142:145], v[134:137], v[166:169], v[142:145]
	v_mfma_f32_16x16x32_bf16 v[142:145], v[138:141], v[170:173], v[142:145]
	v_mfma_f32_16x16x32_bf16 v[114:117], v[118:121], v[174:177], v[114:117]
	v_mfma_f32_16x16x32_bf16 v[114:117], v[130:133], v[178:181], v[114:117]
	v_mfma_f32_16x16x32_bf16 v[110:113], v[134:137], v[174:177], v[110:113]
	v_mfma_f32_16x16x32_bf16 v[110:113], v[138:141], v[178:181], v[110:113]
	v_mfma_f32_16x16x32_bf16 v[98:101], v[118:121], v[182:185], v[98:101]
	v_mfma_f32_16x16x32_bf16 v[98:101], v[130:133], v[186:189], v[98:101]
	v_mfma_f32_16x16x32_bf16 v[94:97], v[134:137], v[182:185], v[94:97]
	v_mfma_f32_16x16x32_bf16 v[94:97], v[138:141], v[186:189], v[94:97]
	v_mfma_f32_16x16x32_bf16 v[82:85], v[118:121], v[190:193], v[82:85]
	v_mfma_f32_16x16x32_bf16 v[82:85], v[130:133], v[194:197], v[82:85]
	v_mfma_f32_16x16x32_bf16 v[78:81], v[134:137], v[190:193], v[78:81]
	v_mfma_f32_16x16x32_bf16 v[78:81], v[138:141], v[194:197], v[78:81]
	s_setprio 0
	s_setprio 1
	v_mfma_f32_16x16x32_bf16 v[126:129], v[146:149], v[166:169], v[126:129]
	v_mfma_f32_16x16x32_bf16 v[126:129], v[154:157], v[170:173], v[126:129]
	v_mfma_f32_16x16x32_bf16 v[122:125], v[158:161], v[166:169], v[122:125]
	v_mfma_f32_16x16x32_bf16 v[122:125], v[162:165], v[170:173], v[122:125]
	v_mfma_f32_16x16x32_bf16 v[106:109], v[146:149], v[174:177], v[106:109]
	v_mfma_f32_16x16x32_bf16 v[106:109], v[154:157], v[178:181], v[106:109]
	v_mfma_f32_16x16x32_bf16 v[102:105], v[158:161], v[174:177], v[102:105]
	v_mfma_f32_16x16x32_bf16 v[102:105], v[162:165], v[178:181], v[102:105]
	v_mfma_f32_16x16x32_bf16 v[90:93], v[146:149], v[182:185], v[90:93]
	v_mfma_f32_16x16x32_bf16 v[90:93], v[154:157], v[186:189], v[90:93]
	v_mfma_f32_16x16x32_bf16 v[86:89], v[158:161], v[182:185], v[86:89]
	v_mfma_f32_16x16x32_bf16 v[86:89], v[162:165], v[186:189], v[86:89]
	v_mfma_f32_16x16x32_bf16 v[74:77], v[146:149], v[190:193], v[74:77]
	v_mfma_f32_16x16x32_bf16 v[74:77], v[154:157], v[194:197], v[74:77]
	v_mfma_f32_16x16x32_bf16 v[70:73], v[158:161], v[190:193], v[70:73]
	v_mfma_f32_16x16x32_bf16 v[70:73], v[162:165], v[194:197], v[70:73]
	s_setprio 0
	s_barrier
; #define PG8_STAGE(bufoff, gbase, voff) do { _Pragma("unroll") for (int _i = 0; _i < 2; ++_i) \
;         __builtin_amdgcn_global_load_lds((const unsigned*)((const char*)(gbase) + (voff)[_i]), (PG8_LAS unsigned*)(lds + (bufoff) + ldsw + _i * 8192), 16, 0, 0); } while (0)
; #define PG8_LDA(dst, b, h) do { _Pragma("unroll") for (int m = 0; m < 4; ++m) _Pragma("unroll") for (int k = 0; k < 2; ++k) dst[m][k] = *(const PG8_LAS bf16x8*)(lds + PG8_SA(b, h) + aoff + m * 2048 + k * 1024); } while (0)
; #define PG8_MMA(ai, bj, At, Bt) do { __builtin_amdgcn_s_setprio(1); _Pragma("unroll") for (int m = 0; m < 4; ++m) _Pragma("unroll") for (int n = 0; n < 2; ++n) _Pragma("unroll") for (int k = 0; k < 2; ++k) \
;         acc[ai][bj][m][n] = __builtin_amdgcn_mfma_f32_16x16x32_bf16(Bt[n][k], At[m][k], acc[ai][bj][m][n], 0, 0, 0); __builtin_amdgcn_s_setprio(0); } while (0)
; #define PG8_WAIT_V(n) asm volatile("s_waitcnt vmcnt(" #n ")" ::: "memory")
; #define PG8_WAIT_L(n) asm volatile("s_waitcnt lgkmcnt(" #n ")" ::: "memory")
; #define PG8_BAR __builtin_amdgcn_s_barrier()
; #define PG8_SCHED __builtin_amdgcn_sched_barrier(0)
; template <class Epi, class Sched, bool ALIGN_EPI = false, bool SP2 = false>
; __device__ __forceinline__ void gemm_phase(PG8_LAS unsigned char* lds, const Gemm g, const Sched& S, const Epi& E) {
;     ...
;             PG8_LDA(At, 1, 1); PG8_STAGE(PG8_SB(1, 0), b3, voffB); PG8_STAGE(PG8_SB(1, 1), b3 + hstep, voffB); PG8_STAGE(PG8_SA(1, 0), a3, voffA);
;             PG8_WAIT_V(8); PG8_WAIT_L(0); PG8_BAR; PG8_MMA(1, 0, At, B0); PG8_MMA(1, 1, At, B1); PG8_BAR; PG8_SCHED;
	s_add_i32 s20, s33, s36
	v_lshl_add_u64 v[202:203], v[202:203], 0, s[92:93]
	s_mov_b32 m0, s20
	ds_read_b128 v[166:169], v201 offset:49152
	ds_read_b128 v[170:173], v201 offset:50176
	ds_read_b128 v[174:177], v201 offset:51200
	ds_read_b128 v[178:181], v201 offset:52224
	ds_read_b128 v[182:185], v201 offset:53248
	ds_read_b128 v[186:189], v201 offset:54272
	ds_read_b128 v[190:193], v201 offset:55296
	ds_read_b128 v[194:197], v201 offset:56320
	global_load_lds_dwordx4 v[202:203], off
	s_add_i32 m0, s20, 0x2000
	s_add_u32 s20, s24, 0x160080
	v_lshl_add_u64 v[202:203], v[214:215], 0, s[92:93]
	s_addc_u32 s21, s25, 0
	s_add_i32 s24, s53, s36
	global_load_lds_dwordx4 v[202:203], off
	v_lshl_add_u64 v[202:203], s[20:21], 0, v[0:1]
	s_mov_b32 m0, s24
	s_nop 0
	global_load_lds_dwordx4 v0, s[20:21]
	v_lshl_add_u64 v[202:203], s[20:21], 0, v[208:209]
	s_add_i32 m0, s24, 0x2000
	s_nop 0
	global_load_lds_dwordx4 v208, s[20:21]
	v_lshl_add_u64 v[202:203], v[216:217], 0, s[92:93]
	s_mov_b32 m0, s42
	s_nop 0
	global_load_lds_dwordx4 v[202:203], off
	v_lshl_add_u64 v[202:203], v[218:219], 0, s[92:93]
	s_mov_b32 m0, s43
	s_nop 0
	global_load_lds_dwordx4 v[202:203], off
	s_waitcnt vmcnt(8)
	s_waitcnt lgkmcnt(0)
	s_barrier
	s_setprio 1
	s_waitcnt lgkmcnt(0)
	v_mfma_f32_16x16x32_bf16 v[66:69], v[118:121], v[166:169], v[66:69]
	v_mfma_f32_16x16x32_bf16 v[66:69], v[130:133], v[170:173], v[66:69]
	v_mfma_f32_16x16x32_bf16 v[62:65], v[134:137], v[166:169], v[62:65]
	v_mfma_f32_16x16x32_bf16 v[62:65], v[138:141], v[170:173], v[62:65]
	v_mfma_f32_16x16x32_bf16 v[50:53], v[118:121], v[174:177], v[50:53]
	v_mfma_f32_16x16x32_bf16 v[50:53], v[130:133], v[178:181], v[50:53]
	v_mfma_f32_16x16x32_bf16 v[46:49], v[134:137], v[174:177], v[46:49]
	v_mfma_f32_16x16x32_bf16 v[46:49], v[138:141], v[178:181], v[46:49]
	v_mfma_f32_16x16x32_bf16 v[34:37], v[118:121], v[182:185], v[34:37]
	v_mfma_f32_16x16x32_bf16 v[34:37], v[130:133], v[186:189], v[34:37]
	v_mfma_f32_16x16x32_bf16 v[30:33], v[134:137], v[182:185], v[30:33]
	v_mfma_f32_16x16x32_bf16 v[30:33], v[138:141], v[186:189], v[30:33]
	v_mfma_f32_16x16x32_bf16 v[18:21], v[118:121], v[190:193], v[18:21]
	v_mfma_f32_16x16x32_bf16 v[18:21], v[130:133], v[194:197], v[18:21]
	v_mfma_f32_16x16x32_bf16 v[10:13], v[134:137], v[190:193], v[10:13]
	v_mfma_f32_16x16x32_bf16 v[10:13], v[138:141], v[194:197], v[10:13]
	s_setprio 0
	s_setprio 1
	v_mfma_f32_16x16x32_bf16 v[58:61], v[146:149], v[166:169], v[58:61]
	v_mfma_f32_16x16x32_bf16 v[58:61], v[154:157], v[170:173], v[58:61]
	v_mfma_f32_16x16x32_bf16 v[54:57], v[158:161], v[166:169], v[54:57]
	v_mfma_f32_16x16x32_bf16 v[54:57], v[162:165], v[170:173], v[54:57]
	v_mfma_f32_16x16x32_bf16 v[42:45], v[146:149], v[174:177], v[42:45]
	v_mfma_f32_16x16x32_bf16 v[42:45], v[154:157], v[178:181], v[42:45]
	v_mfma_f32_16x16x32_bf16 v[38:41], v[158:161], v[174:177], v[38:41]
	v_mfma_f32_16x16x32_bf16 v[38:41], v[162:165], v[178:181], v[38:41]
	v_mfma_f32_16x16x32_bf16 v[26:29], v[146:149], v[182:185], v[26:29]
	v_mfma_f32_16x16x32_bf16 v[26:29], v[154:157], v[186:189], v[26:29]
	v_mfma_f32_16x16x32_bf16 v[22:25], v[158:161], v[182:185], v[22:25]
	v_mfma_f32_16x16x32_bf16 v[22:25], v[162:165], v[186:189], v[22:25]
	v_mfma_f32_16x16x32_bf16 v[6:9], v[146:149], v[190:193], v[6:9]
	v_mfma_f32_16x16x32_bf16 v[6:9], v[154:157], v[194:197], v[6:9]
	v_mfma_f32_16x16x32_bf16 v[2:5], v[158:161], v[190:193], v[2:5]
	v_mfma_f32_16x16x32_bf16 v[2:5], v[162:165], v[194:197], v[2:5]
	s_setprio 0
	s_barrier
	s_add_i32 s52, s52, 2
	s_add_u32 s50, s50, 0x100
	s_addc_u32 s51, s51, 0
	s_cmpk_gt_u32 s52, 0x55
	s_mov_b64 s[20:21], s[22:23]
	s_cbranch_scc0 .LBB0_482
	s_and_b64 vcc, exec, s[14:15]
	s_cbranch_vccz .LBB0_485
	s_barrier

; #define PG8_STAGE(bufoff, gbase, voff) do { _Pragma("unroll") for (int _i = 0; _i < 2; ++_i) \
;         __builtin_amdgcn_global_load_lds((const unsigned*)((const char*)(gbase) + (voff)[_i]), (PG8_LAS unsigned*)(lds + (bufoff) + ldsw + _i * 8192), 16, 0, 0); } while (0)
; #define PG8_LDA(dst, b, h) do { _Pragma("unroll") for (int m = 0; m < 4; ++m) _Pragma("unroll") for (int k = 0; k < 2; ++k) dst[m][k] = *(const PG8_LAS bf16x8*)(lds + PG8_SA(b, h) + aoff + m * 2048 + k * 1024); } while (0)
; #define PG8_LDB(dst, b, h) do { _Pragma("unroll") for (int n = 0; n < 2; ++n) _Pragma("unroll") for (int k = 0; k < 2; ++k) dst[n][k] = *(const PG8_LAS bf16x8*)(lds + PG8_SB(b, h) + boff + n * 2048 + k * 1024); } while (0)
; #define PG8_MMA(ai, bj, At, Bt) do { __builtin_amdgcn_s_setprio(1); _Pragma("unroll") for (int m = 0; m < 4; ++m) _Pragma("unroll") for (int n = 0; n < 2; ++n) _Pragma("unroll") for (int k = 0; k < 2; ++k) \
;         acc[ai][bj][m][n] = __builtin_amdgcn_mfma_f32_16x16x32_bf16(Bt[n][k], At[m][k], acc[ai][bj][m][n], 0, 0, 0); __builtin_amdgcn_s_setprio(0); } while (0)
; #define PG8_WAIT_V(n) asm volatile("s_waitcnt vmcnt(" #n ")" ::: "memory")
; #define PG8_WAIT_L(n) asm volatile("s_waitcnt lgkmcnt(" #n ")" ::: "memory")
; #define PG8_BAR __builtin_amdgcn_s_barrier()
; template <class Epi, class Sched, bool ALIGN_EPI = false, bool SP2 = false>
; __device__ __forceinline__ void gemm_phase(PG8_LAS unsigned char* lds, const Gemm g, const Sched& S, const Epi& E) {
;     ...
;             const bool last = (t == nt - 2);
;             const char* a1 = cA + (size_t)(t + 1) * kstep;
;             const char* a2 = last ? nA : cA + (size_t)(t + 2) * kstep; const char* b2 = last ? nB : cB + (size_t)(t + 2) * kstep;
;             const char* a3 = a2 + kstep; const char* b3 = b2 + kstep;
;             if (last && has_next) S.a_ready(nxt);
;             if constexpr (Epi::MID) { if (t == nt / 2) E.mid(acc, cur, wr, wc, fr, fq); }
;             if constexpr (SP2) {
;             PG8_LDB(B0, 0, 0); PG8_LDB(B1, 0, 1); PG8_SCHED; PG8_LDA(At, 0, 0); PG8_STAGE(PG8_SA(1, 1), a1 + hstep, voffA);
;             PG8_WAIT_V(8); PG8_WAIT_L(0); PG8_BAR; PG8_MMA(0, 0, At, B0); PG8_MMA(0, 1, At, B1); PG8_BAR; PG8_SCHED;
;             PG8_LDA(At, 0, 1); PG8_STAGE(PG8_SB(0, 0), b2, voffB); PG8_STAGE(PG8_SB(0, 1), b2 + hstep, voffB); PG8_STAGE(PG8_SA(0, 0), a2, voffA);
.LBB0_588:
	s_add_u32 s33, s40, 0xfff80080
	s_addc_u32 s44, s41, -1
	s_add_i32 s50, 0, 0x10000
	s_cmp_eq_u32 s49, 28
	s_cselect_b32 s47, s5, s44
	s_cselect_b32 s46, s13, s33
	v_add_u32_e32 v0, s50, v153
	s_cselect_b32 s45, s31, s48
	s_cselect_b32 s44, s35, s43
	s_add_i32 s33, 0, 0x14000
	ds_read_b128 v[134:137], v0
	ds_read_b128 v[138:141], v0 offset:1024
	ds_read_b128 v[142:145], v0 offset:2048
	s_waitcnt lgkmcnt(0)
	ds_read_b128 v[168:171], v0 offset:3072
	v_add_u32_e32 v0, s33, v153
	ds_read_b128 v[172:175], v0
	ds_read_b128 v[176:179], v0 offset:1024
	ds_read_b128 v[180:183], v0 offset:2048
	ds_read_b128 v[184:187], v0 offset:3072
	v_lshl_add_u64 v[192:193], s[40:41], 0, v[166:167]
	s_add_i32 m0, s62, 0xc000
	ds_read_b128 v[188:191], v194
	ds_read_b128 v[196:199], v194 offset:1024
	ds_read_b128 v[200:203], v194 offset:2048
	ds_read_b128 v[206:209], v194 offset:3072
	ds_read_b128 v[210:213], v194 offset:4096
	ds_read_b128 v[214:217], v194 offset:5120
	ds_read_b128 v[218:221], v194 offset:6144
	ds_read_b128 v[222:225], v194 offset:7168
	global_load_lds_dwordx4 v166, s[40:41]
	v_lshl_add_u64 v[192:193], s[40:41], 0, v[164:165]
	s_add_i32 m0, s62, 0xe000
	s_nop 0
	global_load_lds_dwordx4 v164, s[40:41]
	s_waitcnt vmcnt(8)
	s_waitcnt lgkmcnt(0)
	s_barrier
	s_setprio 1
	s_waitcnt lgkmcnt(0)
	v_mfma_f32_16x16x32_bf16 v[74:77], v[134:137], v[188:191], v[74:77]
	v_mfma_f32_16x16x32_bf16 v[74:77], v[138:141], v[196:199], v[74:77]
	v_mfma_f32_16x16x32_bf16 v[62:65], v[142:145], v[188:191], v[62:65]
	v_mfma_f32_16x16x32_bf16 v[62:65], v[168:171], v[196:199], v[62:65]
	v_mfma_f32_16x16x32_bf16 v[58:61], v[134:137], v[200:203], v[58:61]
	v_mfma_f32_16x16x32_bf16 v[58:61], v[138:141], v[206:209], v[58:61]
	v_mfma_f32_16x16x32_bf16 v[54:57], v[142:145], v[200:203], v[54:57]
	v_mfma_f32_16x16x32_bf16 v[54:57], v[168:171], v[206:209], v[54:57]
	v_mfma_f32_16x16x32_bf16 v[50:53], v[134:137], v[210:213], v[50:53]
	v_mfma_f32_16x16x32_bf16 v[50:53], v[138:141], v[214:217], v[50:53]
	v_mfma_f32_16x16x32_bf16 v[46:49], v[142:145], v[210:213], v[46:49]
	v_mfma_f32_16x16x32_bf16 v[46:49], v[168:171], v[214:217], v[46:49]
	v_mfma_f32_16x16x32_bf16 v[42:45], v[134:137], v[218:221], v[42:45]
	v_mfma_f32_16x16x32_bf16 v[42:45], v[138:141], v[222:225], v[42:45]
	v_mfma_f32_16x16x32_bf16 v[38:41], v[142:145], v[218:221], v[38:41]
	v_mfma_f32_16x16x32_bf16 v[38:41], v[168:171], v[222:225], v[38:41]
	s_setprio 0
	s_setprio 1
	v_mfma_f32_16x16x32_bf16 v[130:133], v[172:175], v[188:191], v[130:133]
	v_mfma_f32_16x16x32_bf16 v[130:133], v[176:179], v[196:199], v[130:133]
	v_mfma_f32_16x16x32_bf16 v[126:129], v[180:183], v[188:191], v[126:129]
	v_mfma_f32_16x16x32_bf16 v[126:129], v[184:187], v[196:199], v[126:129]
	v_mfma_f32_16x16x32_bf16 v[122:125], v[172:175], v[200:203], v[122:125]
	v_mfma_f32_16x16x32_bf16 v[122:125], v[176:179], v[206:209], v[122:125]
	v_mfma_f32_16x16x32_bf16 v[118:121], v[180:183], v[200:203], v[118:121]
	v_mfma_f32_16x16x32_bf16 v[118:121], v[184:187], v[206:209], v[118:121]
	v_mfma_f32_16x16x32_bf16 v[114:117], v[172:175], v[210:213], v[114:117]
	v_mfma_f32_16x16x32_bf16 v[114:117], v[176:179], v[214:217], v[114:117]
	v_mfma_f32_16x16x32_bf16 v[110:113], v[180:183], v[210:213], v[110:113]
	v_mfma_f32_16x16x32_bf16 v[110:113], v[184:187], v[214:217], v[110:113]
	v_mfma_f32_16x16x32_bf16 v[106:109], v[172:175], v[218:221], v[106:109]
	v_mfma_f32_16x16x32_bf16 v[106:109], v[176:179], v[222:225], v[106:109]
	v_mfma_f32_16x16x32_bf16 v[102:105], v[180:183], v[218:221], v[102:105]
	v_mfma_f32_16x16x32_bf16 v[102:105], v[184:187], v[222:225], v[102:105]
	s_setprio 0
	s_barrier
	s_add_i32 s50, s50, s61
	v_lshl_add_u64 v[192:193], s[44:45], 0, v[146:147]
	s_mov_b32 m0, s50
	ds_read_b128 v[188:191], v194 offset:16384
	ds_read_b128 v[196:199], v194 offset:17408
	ds_read_b128 v[200:203], v194 offset:18432
	ds_read_b128 v[206:209], v194 offset:19456
	ds_read_b128 v[210:213], v194 offset:20480
	ds_read_b128 v[214:217], v194 offset:21504
	ds_read_b128 v[218:221], v194 offset:22528
	ds_read_b128 v[222:225], v194 offset:23552
	global_load_lds_dwordx4 v146, s[44:45]
	s_add_i32 m0, s50, 0x2000
	s_add_u32 s50, s44, 0x80000
	v_lshl_add_u64 v[226:227], s[44:45], 0, v[150:151]
	s_addc_u32 s51, s45, 0
	s_add_i32 s33, s33, s61
	global_load_lds_dwordx4 v150, s[44:45]
	v_lshl_add_u64 v[228:229], s[50:51], 0, v[146:147]
	s_mov_b32 m0, s33
	v_lshl_add_u64 v[230:231], s[46:47], 0, v[148:149]
	global_load_lds_dwordx4 v146, s[50:51]
	v_lshl_add_u64 v[228:229], s[50:51], 0, v[150:151]
	s_add_i32 m0, s33, 0x2000
	s_nop 0
	global_load_lds_dwordx4 v150, s[50:51]
	v_lshl_add_u64 v[228:229], s[46:47], 0, v[14:15]
	s_mov_b32 m0, s62
	s_nop 0
	global_load_lds_dwordx4 v14, s[46:47]
	s_mov_b32 m0, s63
	s_nop 0
	global_load_lds_dwordx4 v148, s[46:47]
	s_waitcnt vmcnt(8)
	s_waitcnt lgkmcnt(0)
	s_barrier
; #define PG8_STAGE(bufoff, gbase, voff) do { _Pragma("unroll") for (int _i = 0; _i < 2; ++_i) \
;         __builtin_amdgcn_global_load_lds((const unsigned*)((const char*)(gbase) + (voff)[_i]), (PG8_LAS unsigned*)(lds + (bufoff) + ldsw + _i * 8192), 16, 0, 0); } while (0)
; #define PG8_LDA(dst, b, h) do { _Pragma("unroll") for (int m = 0; m < 4; ++m) _Pragma("unroll") for (int k = 0; k < 2; ++k) dst[m][k] = *(const PG8_LAS bf16x8*)(lds + PG8_SA(b, h) + aoff + m * 2048 + k * 1024); } while (0)
; #define PG8_LDB(dst, b, h) do { _Pragma("unroll") for (int n = 0; n < 2; ++n) _Pragma("unroll") for (int k = 0; k < 2; ++k) dst[n][k] = *(const PG8_LAS bf16x8*)(lds + PG8_SB(b, h) + boff + n * 2048 + k * 1024); } while (0)
; #define PG8_MMA(ai, bj, At, Bt) do { __builtin_amdgcn_s_setprio(1); _Pragma("unroll") for (int m = 0; m < 4; ++m) _Pragma("unroll") for (int n = 0; n < 2; ++n) _Pragma("unroll") for (int k = 0; k < 2; ++k) \
;         acc[ai][bj][m][n] = __builtin_amdgcn_mfma_f32_16x16x32_bf16(Bt[n][k], At[m][k], acc[ai][bj][m][n], 0, 0, 0); __builtin_amdgcn_s_setprio(0); } while (0)
; #define PG8_WAIT_V(n) asm volatile("s_waitcnt vmcnt(" #n ")" ::: "memory")
; #define PG8_WAIT_L(n) asm volatile("s_waitcnt lgkmcnt(" #n ")" ::: "memory")
; #define PG8_BAR __builtin_amdgcn_s_barrier()
; #define PG8_SCHED __builtin_amdgcn_sched_barrier(0)
; template <class Epi, class Sched, bool ALIGN_EPI = false, bool SP2 = false>
; __device__ __forceinline__ void gemm_phase(PG8_LAS unsigned char* lds, const Gemm g, const Sched& S, const Epi& E) {
;     ...
;             PG8_WAIT_V(8); PG8_WAIT_L(0); PG8_BAR; PG8_MMA(1, 0, At, B0); PG8_MMA(1, 1, At, B1); PG8_BAR; PG8_SCHED;
;             PG8_LDB(B0, 1, 0); PG8_LDB(B1, 1, 1); PG8_SCHED; PG8_LDA(At, 1, 0); PG8_STAGE(PG8_SA(0, 1), a2 + hstep, voffA);
;             PG8_WAIT_V(8); PG8_WAIT_L(0); PG8_BAR; PG8_MMA(0, 0, At, B0); PG8_MMA(0, 1, At, B1); PG8_BAR; PG8_SCHED;
	s_setprio 1
	s_waitcnt lgkmcnt(0)
	v_mfma_f32_16x16x32_bf16 v[34:37], v[134:137], v[188:191], v[34:37]
	v_mfma_f32_16x16x32_bf16 v[34:37], v[138:141], v[196:199], v[34:37]
	v_mfma_f32_16x16x32_bf16 v[30:33], v[142:145], v[188:191], v[30:33]
	v_mfma_f32_16x16x32_bf16 v[30:33], v[168:171], v[196:199], v[30:33]
	v_mfma_f32_16x16x32_bf16 v[26:29], v[134:137], v[200:203], v[26:29]
	v_mfma_f32_16x16x32_bf16 v[26:29], v[138:141], v[206:209], v[26:29]
	v_mfma_f32_16x16x32_bf16 v[22:25], v[142:145], v[200:203], v[22:25]
	v_mfma_f32_16x16x32_bf16 v[22:25], v[168:171], v[206:209], v[22:25]
	v_mfma_f32_16x16x32_bf16 v[18:21], v[134:137], v[210:213], v[18:21]
	v_mfma_f32_16x16x32_bf16 v[18:21], v[138:141], v[214:217], v[18:21]
	v_mfma_f32_16x16x32_bf16 v[10:13], v[142:145], v[210:213], v[10:13]
	v_mfma_f32_16x16x32_bf16 v[10:13], v[168:171], v[214:217], v[10:13]
	v_mfma_f32_16x16x32_bf16 v[6:9], v[134:137], v[218:221], v[6:9]
	v_mfma_f32_16x16x32_bf16 v[6:9], v[138:141], v[222:225], v[6:9]
	v_mfma_f32_16x16x32_bf16 v[2:5], v[142:145], v[218:221], v[2:5]
	v_mfma_f32_16x16x32_bf16 v[2:5], v[168:171], v[222:225], v[2:5]
	s_setprio 0
	s_setprio 1
	v_mfma_f32_16x16x32_bf16 v[98:101], v[172:175], v[188:191], v[98:101]
	v_mfma_f32_16x16x32_bf16 v[98:101], v[176:179], v[196:199], v[98:101]
	v_mfma_f32_16x16x32_bf16 v[94:97], v[180:183], v[188:191], v[94:97]
	v_mfma_f32_16x16x32_bf16 v[94:97], v[184:187], v[196:199], v[94:97]
	v_mfma_f32_16x16x32_bf16 v[90:93], v[172:175], v[200:203], v[90:93]
	v_mfma_f32_16x16x32_bf16 v[90:93], v[176:179], v[206:209], v[90:93]
	v_mfma_f32_16x16x32_bf16 v[86:89], v[180:183], v[200:203], v[86:89]
	v_mfma_f32_16x16x32_bf16 v[86:89], v[184:187], v[206:209], v[86:89]
	v_mfma_f32_16x16x32_bf16 v[82:85], v[172:175], v[210:213], v[82:85]
	v_mfma_f32_16x16x32_bf16 v[82:85], v[176:179], v[214:217], v[82:85]
	v_mfma_f32_16x16x32_bf16 v[78:81], v[180:183], v[210:213], v[78:81]
	v_mfma_f32_16x16x32_bf16 v[78:81], v[184:187], v[214:217], v[78:81]
	v_mfma_f32_16x16x32_bf16 v[70:73], v[172:175], v[218:221], v[70:73]
	v_mfma_f32_16x16x32_bf16 v[70:73], v[176:179], v[222:225], v[70:73]
	v_mfma_f32_16x16x32_bf16 v[66:69], v[180:183], v[218:221], v[66:69]
	v_mfma_f32_16x16x32_bf16 v[66:69], v[184:187], v[222:225], v[66:69]
	s_setprio 0
	s_barrier
	s_add_i32 s33, 0, 0x18000
	v_add_u32_e32 v0, s33, v153
	s_add_i32 s50, 0, 0x1c000
	ds_read_b128 v[134:137], v0
	ds_read_b128 v[138:141], v0 offset:1024
	ds_read_b128 v[142:145], v0 offset:2048
	ds_read_b128 v[168:171], v0 offset:3072
	v_add_u32_e32 v0, s50, v153
	ds_read_b128 v[172:175], v0
	ds_read_b128 v[176:179], v0 offset:1024
	ds_read_b128 v[180:183], v0 offset:2048
	ds_read_b128 v[184:187], v0 offset:3072
	s_add_u32 s46, s46, 0x80000
	s_addc_u32 s47, s47, 0
	s_mov_b32 m0, s64
	v_lshl_add_u64 v[232:233], s[46:47], 0, v[14:15]
	ds_read_b128 v[188:191], v194 offset:32768
	ds_read_b128 v[196:199], v194 offset:33792
	ds_read_b128 v[200:203], v194 offset:34816
	ds_read_b128 v[206:209], v194 offset:35840
	ds_read_b128 v[210:213], v194 offset:36864
	ds_read_b128 v[214:217], v194 offset:37888
	ds_read_b128 v[218:221], v194 offset:38912
	ds_read_b128 v[222:225], v194 offset:39936
	global_load_lds_dwordx4 v14, s[46:47]
	v_lshl_add_u64 v[232:233], s[46:47], 0, v[148:149]
	s_mov_b32 m0, s65
	s_nop 0
	global_load_lds_dwordx4 v148, s[46:47]
	s_waitcnt vmcnt(8)
	s_waitcnt lgkmcnt(0)
	s_barrier
	s_setprio 1
	s_waitcnt lgkmcnt(0)
	v_mfma_f32_16x16x32_bf16 v[74:77], v[134:137], v[188:191], v[74:77]
	v_mfma_f32_16x16x32_bf16 v[74:77], v[138:141], v[196:199], v[74:77]
	v_mfma_f32_16x16x32_bf16 v[62:65], v[142:145], v[188:191], v[62:65]
	v_mfma_f32_16x16x32_bf16 v[62:65], v[168:171], v[196:199], v[62:65]
	v_mfma_f32_16x16x32_bf16 v[58:61], v[134:137], v[200:203], v[58:61]
	v_mfma_f32_16x16x32_bf16 v[58:61], v[138:141], v[206:209], v[58:61]
	v_mfma_f32_16x16x32_bf16 v[54:57], v[142:145], v[200:203], v[54:57]
	v_mfma_f32_16x16x32_bf16 v[54:57], v[168:171], v[206:209], v[54:57]
	v_mfma_f32_16x16x32_bf16 v[50:53], v[134:137], v[210:213], v[50:53]
	v_mfma_f32_16x16x32_bf16 v[50:53], v[138:141], v[214:217], v[50:53]
	v_mfma_f32_16x16x32_bf16 v[46:49], v[142:145], v[210:213], v[46:49]
	v_mfma_f32_16x16x32_bf16 v[46:49], v[168:171], v[214:217], v[46:49]
	v_mfma_f32_16x16x32_bf16 v[42:45], v[134:137], v[218:221], v[42:45]
	v_mfma_f32_16x16x32_bf16 v[42:45], v[138:141], v[222:225], v[42:45]
	v_mfma_f32_16x16x32_bf16 v[38:41], v[142:145], v[218:221], v[38:41]
	v_mfma_f32_16x16x32_bf16 v[38:41], v[168:171], v[222:225], v[38:41]
	s_setprio 0
	s_setprio 1
	v_mfma_f32_16x16x32_bf16 v[130:133], v[172:175], v[188:191], v[130:133]
	v_mfma_f32_16x16x32_bf16 v[130:133], v[176:179], v[196:199], v[130:133]
	v_mfma_f32_16x16x32_bf16 v[126:129], v[180:183], v[188:191], v[126:129]
	v_mfma_f32_16x16x32_bf16 v[126:129], v[184:187], v[196:199], v[126:129]
	v_mfma_f32_16x16x32_bf16 v[122:125], v[172:175], v[200:203], v[122:125]
	v_mfma_f32_16x16x32_bf16 v[122:125], v[176:179], v[206:209], v[122:125]
	v_mfma_f32_16x16x32_bf16 v[118:121], v[180:183], v[200:203], v[118:121]
	v_mfma_f32_16x16x32_bf16 v[118:121], v[184:187], v[206:209], v[118:121]
	v_mfma_f32_16x16x32_bf16 v[114:117], v[172:175], v[210:213], v[114:117]
	v_mfma_f32_16x16x32_bf16 v[114:117], v[176:179], v[214:217], v[114:117]
	v_mfma_f32_16x16x32_bf16 v[110:113], v[180:183], v[210:213], v[110:113]
	v_mfma_f32_16x16x32_bf16 v[110:113], v[184:187], v[214:217], v[110:113]
	v_mfma_f32_16x16x32_bf16 v[106:109], v[172:175], v[218:221], v[106:109]
	v_mfma_f32_16x16x32_bf16 v[106:109], v[176:179], v[222:225], v[106:109]
	v_mfma_f32_16x16x32_bf16 v[102:105], v[180:183], v[218:221], v[102:105]
	v_mfma_f32_16x16x32_bf16 v[102:105], v[184:187], v[222:225], v[102:105]
	s_setprio 0
	s_barrier
; #define PG8_STAGE(bufoff, gbase, voff) do { _Pragma("unroll") for (int _i = 0; _i < 2; ++_i) \
;         __builtin_amdgcn_global_load_lds((const unsigned*)((const char*)(gbase) + (voff)[_i]), (PG8_LAS unsigned*)(lds + (bufoff) + ldsw + _i * 8192), 16, 0, 0); } while (0)
; #define PG8_LDA(dst, b, h) do { _Pragma("unroll") for (int m = 0; m < 4; ++m) _Pragma("unroll") for (int k = 0; k < 2; ++k) dst[m][k] = *(const PG8_LAS bf16x8*)(lds + PG8_SA(b, h) + aoff + m * 2048 + k * 1024); } while (0)
; #define PG8_MMA(ai, bj, At, Bt) do { __builtin_amdgcn_s_setprio(1); _Pragma("unroll") for (int m = 0; m < 4; ++m) _Pragma("unroll") for (int n = 0; n < 2; ++n) _Pragma("unroll") for (int k = 0; k < 2; ++k) \
;         acc[ai][bj][m][n] = __builtin_amdgcn_mfma_f32_16x16x32_bf16(Bt[n][k], At[m][k], acc[ai][bj][m][n], 0, 0, 0); __builtin_amdgcn_s_setprio(0); } while (0)
; #define PG8_WAIT_V(n) asm volatile("s_waitcnt vmcnt(" #n ")" ::: "memory")
; #define PG8_WAIT_L(n) asm volatile("s_waitcnt lgkmcnt(" #n ")" ::: "memory")
; #define PG8_BAR __builtin_amdgcn_s_barrier()
; #define PG8_SCHED __builtin_amdgcn_sched_barrier(0)
; template <class Epi, class Sched, bool ALIGN_EPI = false, bool SP2 = false>
; __device__ __forceinline__ void gemm_phase(PG8_LAS unsigned char* lds, const Gemm g, const Sched& S, const Epi& E) {
;     ...
;             PG8_LDA(At, 1, 1); PG8_STAGE(PG8_SB(1, 0), b3, voffB); PG8_STAGE(PG8_SB(1, 1), b3 + hstep, voffB); PG8_STAGE(PG8_SA(1, 0), a3, voffA);
;             PG8_WAIT_V(8); PG8_WAIT_L(0); PG8_BAR; PG8_MMA(1, 0, At, B0); PG8_MMA(1, 1, At, B1); PG8_BAR; PG8_SCHED;
	s_add_i32 s33, s33, s61
	v_lshl_add_u64 v[192:193], v[192:193], 0, s[92:93]
	s_mov_b32 m0, s33
	ds_read_b128 v[188:191], v194 offset:49152
	ds_read_b128 v[196:199], v194 offset:50176
	ds_read_b128 v[200:203], v194 offset:51200
	ds_read_b128 v[206:209], v194 offset:52224
	ds_read_b128 v[210:213], v194 offset:53248
	ds_read_b128 v[214:217], v194 offset:54272
	ds_read_b128 v[218:221], v194 offset:55296
	ds_read_b128 v[222:225], v194 offset:56320
	global_load_lds_dwordx4 v[192:193], off
	s_add_i32 m0, s33, 0x2000
	s_add_u32 s44, s44, 0x80080
	v_lshl_add_u64 v[192:193], v[226:227], 0, s[92:93]
	s_addc_u32 s45, s45, 0
	s_add_i32 s33, s50, s61
	global_load_lds_dwordx4 v[192:193], off
	v_lshl_add_u64 v[192:193], s[44:45], 0, v[146:147]
	s_mov_b32 m0, s33
	s_nop 0
	global_load_lds_dwordx4 v146, s[44:45]
	v_lshl_add_u64 v[192:193], s[44:45], 0, v[150:151]
	s_add_i32 m0, s33, 0x2000
	s_nop 0
	global_load_lds_dwordx4 v150, s[44:45]
	v_lshl_add_u64 v[192:193], v[228:229], 0, s[92:93]
	s_mov_b32 m0, s68
	s_nop 0
	global_load_lds_dwordx4 v[192:193], off
	v_lshl_add_u64 v[192:193], v[230:231], 0, s[92:93]
	s_mov_b32 m0, s69
	s_nop 0
	global_load_lds_dwordx4 v[192:193], off
	s_waitcnt vmcnt(8)
	s_waitcnt lgkmcnt(0)
	s_barrier
	s_setprio 1
	s_waitcnt lgkmcnt(0)
	v_mfma_f32_16x16x32_bf16 v[34:37], v[134:137], v[188:191], v[34:37]
	v_mfma_f32_16x16x32_bf16 v[34:37], v[138:141], v[196:199], v[34:37]
	v_mfma_f32_16x16x32_bf16 v[30:33], v[142:145], v[188:191], v[30:33]
	v_mfma_f32_16x16x32_bf16 v[30:33], v[168:171], v[196:199], v[30:33]
	v_mfma_f32_16x16x32_bf16 v[26:29], v[134:137], v[200:203], v[26:29]
	v_mfma_f32_16x16x32_bf16 v[26:29], v[138:141], v[206:209], v[26:29]
	v_mfma_f32_16x16x32_bf16 v[22:25], v[142:145], v[200:203], v[22:25]
	v_mfma_f32_16x16x32_bf16 v[22:25], v[168:171], v[206:209], v[22:25]
	v_mfma_f32_16x16x32_bf16 v[18:21], v[134:137], v[210:213], v[18:21]
	v_mfma_f32_16x16x32_bf16 v[18:21], v[138:141], v[214:217], v[18:21]
	v_mfma_f32_16x16x32_bf16 v[10:13], v[142:145], v[210:213], v[10:13]
	v_mfma_f32_16x16x32_bf16 v[10:13], v[168:171], v[214:217], v[10:13]
	v_mfma_f32_16x16x32_bf16 v[6:9], v[134:137], v[218:221], v[6:9]
	v_mfma_f32_16x16x32_bf16 v[6:9], v[138:141], v[222:225], v[6:9]
	v_mfma_f32_16x16x32_bf16 v[2:5], v[142:145], v[218:221], v[2:5]
	v_mfma_f32_16x16x32_bf16 v[2:5], v[168:171], v[222:225], v[2:5]
	s_setprio 0
	s_setprio 1
	v_mfma_f32_16x16x32_bf16 v[98:101], v[172:175], v[188:191], v[98:101]
	v_mfma_f32_16x16x32_bf16 v[98:101], v[176:179], v[196:199], v[98:101]
	v_mfma_f32_16x16x32_bf16 v[94:97], v[180:183], v[188:191], v[94:97]
	v_mfma_f32_16x16x32_bf16 v[94:97], v[184:187], v[196:199], v[94:97]
	v_mfma_f32_16x16x32_bf16 v[90:93], v[172:175], v[200:203], v[90:93]
	v_mfma_f32_16x16x32_bf16 v[90:93], v[176:179], v[206:209], v[90:93]
	v_mfma_f32_16x16x32_bf16 v[86:89], v[180:183], v[200:203], v[86:89]
	v_mfma_f32_16x16x32_bf16 v[86:89], v[184:187], v[206:209], v[86:89]
	v_mfma_f32_16x16x32_bf16 v[82:85], v[172:175], v[210:213], v[82:85]
	v_mfma_f32_16x16x32_bf16 v[82:85], v[176:179], v[214:217], v[82:85]
	v_mfma_f32_16x16x32_bf16 v[78:81], v[180:183], v[210:213], v[78:81]
	v_mfma_f32_16x16x32_bf16 v[78:81], v[184:187], v[214:217], v[78:81]
	v_mfma_f32_16x16x32_bf16 v[70:73], v[172:175], v[218:221], v[70:73]
	v_mfma_f32_16x16x32_bf16 v[70:73], v[176:179], v[222:225], v[70:73]
	v_mfma_f32_16x16x32_bf16 v[66:69], v[180:183], v[218:221], v[66:69]
	v_mfma_f32_16x16x32_bf16 v[66:69], v[184:187], v[222:225], v[66:69]
	s_setprio 0
	s_barrier
	s_add_i32 s49, s49, 2
	s_add_u32 s43, s43, 0x100
	s_addc_u32 s48, s48, 0
	s_add_u32 s40, s40, 0x100
	s_addc_u32 s41, s41, 0
	s_cmp_gt_u32 s49, 29
	s_cbranch_scc0 .LBB0_588
	s_and_b64 vcc, exec, s[18:19]
	s_cbranch_vccz .LBB0_591
	s_barrier

; #define PG8_STAGE(bufoff, gbase, voff) do { _Pragma("unroll") for (int _i = 0; _i < 2; ++_i) \
;         __builtin_amdgcn_global_load_lds((const unsigned*)((const char*)(gbase) + (voff)[_i]), (PG8_LAS unsigned*)(lds + (bufoff) + ldsw + _i * 8192), 16, 0, 0); } while (0)
; #define PG8_LDA(dst, b, h) do { _Pragma("unroll") for (int m = 0; m < 4; ++m) _Pragma("unroll") for (int k = 0; k < 2; ++k) dst[m][k] = *(const PG8_LAS bf16x8*)(lds + PG8_SA(b, h) + aoff + m * 2048 + k * 1024); } while (0)
; #define PG8_LDB(dst, b, h) do { _Pragma("unroll") for (int n = 0; n < 2; ++n) _Pragma("unroll") for (int k = 0; k < 2; ++k) dst[n][k] = *(const PG8_LAS bf16x8*)(lds + PG8_SB(b, h) + boff + n * 2048 + k * 1024); } while (0)
; #define PG8_MMA(ai, bj, At, Bt) do { __builtin_amdgcn_s_setprio(1); _Pragma("unroll") for (int m = 0; m < 4; ++m) _Pragma("unroll") for (int n = 0; n < 2; ++n) _Pragma("unroll") for (int k = 0; k < 2; ++k) \
;         acc[ai][bj][m][n] = __builtin_amdgcn_mfma_f32_16x16x32_bf16(Bt[n][k], At[m][k], acc[ai][bj][m][n], 0, 0, 0); __builtin_amdgcn_s_setprio(0); } while (0)
; #define PG8_WAIT_V(n) asm volatile("s_waitcnt vmcnt(" #n ")" ::: "memory")
; #define PG8_WAIT_L(n) asm volatile("s_waitcnt lgkmcnt(" #n ")" ::: "memory")
; #define PG8_BAR __builtin_amdgcn_s_barrier()
; template <class Epi, class Sched, bool ALIGN_EPI = false, bool SP2 = false>
; __device__ __forceinline__ void gemm_phase(PG8_LAS unsigned char* lds, const Gemm g, const Sched& S, const Epi& E) {
;     ...
;             const bool last = (t == nt - 2);
;             const char* a1 = cA + (size_t)(t + 1) * kstep;
;             const char* a2 = last ? nA : cA + (size_t)(t + 2) * kstep; const char* b2 = last ? nB : cB + (size_t)(t + 2) * kstep;
;             const char* a3 = a2 + kstep; const char* b3 = b2 + kstep;
;             if (last && has_next) S.a_ready(nxt);
;             if constexpr (Epi::MID) { if (t == nt / 2) E.mid(acc, cur, wr, wc, fr, fq); }
;             if constexpr (SP2) {
;             PG8_LDB(B0, 0, 0); PG8_LDB(B1, 0, 1); PG8_SCHED; PG8_LDA(At, 0, 0); PG8_STAGE(PG8_SA(1, 1), a1 + hstep, voffA);
;             PG8_WAIT_V(8); PG8_WAIT_L(0); PG8_BAR; PG8_MMA(0, 0, At, B0); PG8_MMA(0, 1, At, B1); PG8_BAR; PG8_SCHED;
;             PG8_LDA(At, 0, 1); PG8_STAGE(PG8_SB(0, 0), b2, voffB); PG8_STAGE(PG8_SB(0, 1), b2 + hstep, voffB); PG8_STAGE(PG8_SA(0, 0), a2, voffA);
.LBB0_1091:
	s_add_u32 s6, s30, s34
	s_addc_u32 s7, s31, s35
	s_add_u32 s6, s6, 0x100
	s_addc_u32 s7, s7, 0
	s_add_u32 s33, s59, s34
	s_addc_u32 s62, s60, s35
	s_cmpk_eq_i32 s34, 0xf00
	s_cselect_b32 s37, s55, s7
	s_cselect_b32 s36, s56, s6
	s_cselect_b32 s7, s57, s62
	s_cselect_b32 s6, s58, s33
	s_add_i32 s33, 0, 0x10000
	v_add_u32_e32 v0, s33, v249
	s_add_i32 s64, 0, 0x14000
	ds_read_b128 v[134:137], v0
	ds_read_b128 v[138:141], v0 offset:1024
	ds_read_b128 v[142:145], v0 offset:2048
	ds_read_b128 v[146:149], v0 offset:3072
	v_add_u32_e32 v0, s64, v249
	ds_read_b128 v[150:153], v0
	ds_read_b128 v[154:157], v0 offset:1024
	ds_read_b128 v[158:161], v0 offset:2048
	ds_read_b128 v[162:165], v0 offset:3072
	v_lshl_add_u64 v[2:3], v[172:173], 0, s[34:35]
	s_add_i32 m0, s15, 0xc000
	ds_read_b128 v[176:179], v202
	ds_read_b128 v[180:183], v202 offset:1024
	ds_read_b128 v[184:187], v202 offset:2048
	ds_read_b128 v[188:191], v202 offset:3072
	ds_read_b128 v[192:195], v202 offset:4096
	ds_read_b128 v[218:221], v202 offset:5120
	ds_read_b128 v[222:225], v202 offset:6144
	ds_read_b128 v[226:229], v202 offset:7168
	global_load_lds_dwordx4 v[2:3], off
	v_lshl_add_u64 v[2:3], v[170:171], 0, s[34:35]
	s_add_i32 m0, s15, 0xe000
	s_nop 0
	global_load_lds_dwordx4 v[2:3], off
	s_waitcnt vmcnt(8)
	s_waitcnt lgkmcnt(0)
	s_barrier
	s_setprio 1
	s_waitcnt lgkmcnt(0)
	v_mfma_f32_16x16x32_bf16 v[130:133], v[134:137], v[176:179], v[130:133]
	v_mfma_f32_16x16x32_bf16 v[130:133], v[138:141], v[180:183], v[130:133]
	v_mfma_f32_16x16x32_bf16 v[126:129], v[142:145], v[176:179], v[126:129]
	v_mfma_f32_16x16x32_bf16 v[126:129], v[146:149], v[180:183], v[126:129]
	v_mfma_f32_16x16x32_bf16 v[114:117], v[134:137], v[184:187], v[114:117]
	v_mfma_f32_16x16x32_bf16 v[114:117], v[138:141], v[188:191], v[114:117]
	v_mfma_f32_16x16x32_bf16 v[110:113], v[142:145], v[184:187], v[110:113]
	v_mfma_f32_16x16x32_bf16 v[110:113], v[146:149], v[188:191], v[110:113]
	v_mfma_f32_16x16x32_bf16 v[98:101], v[134:137], v[192:195], v[98:101]
	v_mfma_f32_16x16x32_bf16 v[98:101], v[138:141], v[218:221], v[98:101]
	v_mfma_f32_16x16x32_bf16 v[94:97], v[142:145], v[192:195], v[94:97]
	v_mfma_f32_16x16x32_bf16 v[94:97], v[146:149], v[218:221], v[94:97]
	v_mfma_f32_16x16x32_bf16 v[82:85], v[134:137], v[222:225], v[82:85]
	v_mfma_f32_16x16x32_bf16 v[82:85], v[138:141], v[226:229], v[82:85]
	v_mfma_f32_16x16x32_bf16 v[78:81], v[142:145], v[222:225], v[78:81]
	v_mfma_f32_16x16x32_bf16 v[78:81], v[146:149], v[226:229], v[78:81]
	s_setprio 0
	s_setprio 1
	v_mfma_f32_16x16x32_bf16 v[122:125], v[150:153], v[176:179], v[122:125]
	v_mfma_f32_16x16x32_bf16 v[122:125], v[154:157], v[180:183], v[122:125]
	v_mfma_f32_16x16x32_bf16 v[118:121], v[158:161], v[176:179], v[118:121]
	v_mfma_f32_16x16x32_bf16 v[118:121], v[162:165], v[180:183], v[118:121]
	v_mfma_f32_16x16x32_bf16 v[106:109], v[150:153], v[184:187], v[106:109]
	v_mfma_f32_16x16x32_bf16 v[106:109], v[154:157], v[188:191], v[106:109]
	v_mfma_f32_16x16x32_bf16 v[102:105], v[158:161], v[184:187], v[102:105]
	v_mfma_f32_16x16x32_bf16 v[102:105], v[162:165], v[188:191], v[102:105]
	v_mfma_f32_16x16x32_bf16 v[90:93], v[150:153], v[192:195], v[90:93]
	v_mfma_f32_16x16x32_bf16 v[90:93], v[154:157], v[218:221], v[90:93]
	v_mfma_f32_16x16x32_bf16 v[86:89], v[158:161], v[192:195], v[86:89]
	v_mfma_f32_16x16x32_bf16 v[86:89], v[162:165], v[218:221], v[86:89]
	v_mfma_f32_16x16x32_bf16 v[74:77], v[150:153], v[222:225], v[74:77]
	v_mfma_f32_16x16x32_bf16 v[74:77], v[154:157], v[226:229], v[74:77]
	v_mfma_f32_16x16x32_bf16 v[70:73], v[158:161], v[222:225], v[70:73]
	v_mfma_f32_16x16x32_bf16 v[70:73], v[162:165], v[226:229], v[70:73]
	s_setprio 0
	s_barrier
	s_add_i32 s33, s33, s43
	v_lshl_add_u64 v[196:197], s[6:7], 0, v[208:209]
	s_mov_b32 m0, s33
	ds_read_b128 v[176:179], v202 offset:16384
	ds_read_b128 v[180:183], v202 offset:17408
	ds_read_b128 v[184:187], v202 offset:18432
	ds_read_b128 v[188:191], v202 offset:19456
	ds_read_b128 v[192:195], v202 offset:20480
	ds_read_b128 v[218:221], v202 offset:21504
	ds_read_b128 v[222:225], v202 offset:22528
	ds_read_b128 v[226:229], v202 offset:23552
	global_load_lds_dwordx4 v208, s[6:7]
	s_add_i32 m0, s33, 0x2000
	s_add_u32 s62, s6, 0x80000
	v_lshl_add_u64 v[230:231], s[6:7], 0, v[212:213]
	s_addc_u32 s63, s7, 0
	s_add_i32 s33, s64, s43
	global_load_lds_dwordx4 v212, s[6:7]
	v_lshl_add_u64 v[2:3], s[62:63], 0, v[208:209]
	s_mov_b32 m0, s33
	v_lshl_add_u64 v[232:233], s[36:37], 0, v[206:207]
	global_load_lds_dwordx4 v208, s[62:63]
	v_lshl_add_u64 v[2:3], s[62:63], 0, v[212:213]
	s_add_i32 m0, s33, 0x2000
	v_lshl_add_u64 v[234:235], s[36:37], 0, v[210:211]
	global_load_lds_dwordx4 v212, s[62:63]
	s_mov_b32 m0, s15
	s_nop 0
	global_load_lds_dwordx4 v206, s[36:37]
	s_mov_b32 m0, s44
	s_nop 0
	global_load_lds_dwordx4 v210, s[36:37]
	s_waitcnt vmcnt(8)
	s_waitcnt lgkmcnt(0)
	s_barrier
; #define PG8_STAGE(bufoff, gbase, voff) do { _Pragma("unroll") for (int _i = 0; _i < 2; ++_i) \
;         __builtin_amdgcn_global_load_lds((const unsigned*)((const char*)(gbase) + (voff)[_i]), (PG8_LAS unsigned*)(lds + (bufoff) + ldsw + _i * 8192), 16, 0, 0); } while (0)
; #define PG8_LDA(dst, b, h) do { _Pragma("unroll") for (int m = 0; m < 4; ++m) _Pragma("unroll") for (int k = 0; k < 2; ++k) dst[m][k] = *(const PG8_LAS bf16x8*)(lds + PG8_SA(b, h) + aoff + m * 2048 + k * 1024); } while (0)
; #define PG8_LDB(dst, b, h) do { _Pragma("unroll") for (int n = 0; n < 2; ++n) _Pragma("unroll") for (int k = 0; k < 2; ++k) dst[n][k] = *(const PG8_LAS bf16x8*)(lds + PG8_SB(b, h) + boff + n * 2048 + k * 1024); } while (0)
; #define PG8_MMA(ai, bj, At, Bt) do { __builtin_amdgcn_s_setprio(1); _Pragma("unroll") for (int m = 0; m < 4; ++m) _Pragma("unroll") for (int n = 0; n < 2; ++n) _Pragma("unroll") for (int k = 0; k < 2; ++k) \
;         acc[ai][bj][m][n] = __builtin_amdgcn_mfma_f32_16x16x32_bf16(Bt[n][k], At[m][k], acc[ai][bj][m][n], 0, 0, 0); __builtin_amdgcn_s_setprio(0); } while (0)
; #define PG8_WAIT_V(n) asm volatile("s_waitcnt vmcnt(" #n ")" ::: "memory")
; #define PG8_WAIT_L(n) asm volatile("s_waitcnt lgkmcnt(" #n ")" ::: "memory")
; #define PG8_BAR __builtin_amdgcn_s_barrier()
; #define PG8_SCHED __builtin_amdgcn_sched_barrier(0)
; template <class Epi, class Sched, bool ALIGN_EPI = false, bool SP2 = false>
; __device__ __forceinline__ void gemm_phase(PG8_LAS unsigned char* lds, const Gemm g, const Sched& S, const Epi& E) {
;     ...
;             PG8_WAIT_V(8); PG8_WAIT_L(0); PG8_BAR; PG8_MMA(1, 0, At, B0); PG8_MMA(1, 1, At, B1); PG8_BAR; PG8_SCHED;
;             PG8_LDB(B0, 1, 0); PG8_LDB(B1, 1, 1); PG8_SCHED; PG8_LDA(At, 1, 0); PG8_STAGE(PG8_SA(0, 1), a2 + hstep, voffA);
;             PG8_WAIT_V(8); PG8_WAIT_L(0); PG8_BAR; PG8_MMA(0, 0, At, B0); PG8_MMA(0, 1, At, B1); PG8_BAR; PG8_SCHED;
	s_setprio 1
	s_waitcnt lgkmcnt(0)
	v_mfma_f32_16x16x32_bf16 v[66:69], v[134:137], v[176:179], v[66:69]
	v_mfma_f32_16x16x32_bf16 v[66:69], v[138:141], v[180:183], v[66:69]
	v_mfma_f32_16x16x32_bf16 v[62:65], v[142:145], v[176:179], v[62:65]
	v_mfma_f32_16x16x32_bf16 v[62:65], v[146:149], v[180:183], v[62:65]
	v_mfma_f32_16x16x32_bf16 v[50:53], v[134:137], v[184:187], v[50:53]
	v_mfma_f32_16x16x32_bf16 v[50:53], v[138:141], v[188:191], v[50:53]
	v_mfma_f32_16x16x32_bf16 v[46:49], v[142:145], v[184:187], v[46:49]
	v_mfma_f32_16x16x32_bf16 v[46:49], v[146:149], v[188:191], v[46:49]
	v_mfma_f32_16x16x32_bf16 v[34:37], v[134:137], v[192:195], v[34:37]
	v_mfma_f32_16x16x32_bf16 v[34:37], v[138:141], v[218:221], v[34:37]
	v_mfma_f32_16x16x32_bf16 v[30:33], v[142:145], v[192:195], v[30:33]
	v_mfma_f32_16x16x32_bf16 v[30:33], v[146:149], v[218:221], v[30:33]
	v_mfma_f32_16x16x32_bf16 v[18:21], v[134:137], v[222:225], v[18:21]
	v_mfma_f32_16x16x32_bf16 v[18:21], v[138:141], v[226:229], v[18:21]
	v_mfma_f32_16x16x32_bf16 v[12:15], v[142:145], v[222:225], v[12:15]
	v_mfma_f32_16x16x32_bf16 v[12:15], v[146:149], v[226:229], v[12:15]
	s_setprio 0
	s_setprio 1
	v_mfma_f32_16x16x32_bf16 v[58:61], v[150:153], v[176:179], v[58:61]
	v_mfma_f32_16x16x32_bf16 v[54:57], v[158:161], v[176:179], v[54:57]
	v_mfma_f32_16x16x32_bf16 v[42:45], v[150:153], v[184:187], v[42:45]
	v_mfma_f32_16x16x32_bf16 v[38:41], v[158:161], v[184:187], v[38:41]
	v_mfma_f32_16x16x32_bf16 v[26:29], v[150:153], v[192:195], v[26:29]
	v_mfma_f32_16x16x32_bf16 v[22:25], v[158:161], v[192:195], v[22:25]
	v_mfma_f32_16x16x32_bf16 v[8:11], v[150:153], v[222:225], v[8:11]
	v_mfma_f32_16x16x32_bf16 v[2:5], v[158:161], v[222:225], v[4:7]
	v_mfma_f32_16x16x32_bf16 v[58:61], v[154:157], v[180:183], v[58:61]
	v_mfma_f32_16x16x32_bf16 v[54:57], v[162:165], v[180:183], v[54:57]
	v_mfma_f32_16x16x32_bf16 v[42:45], v[154:157], v[188:191], v[42:45]
	v_mfma_f32_16x16x32_bf16 v[38:41], v[162:165], v[188:191], v[38:41]
	v_mfma_f32_16x16x32_bf16 v[26:29], v[154:157], v[218:221], v[26:29]
	v_mfma_f32_16x16x32_bf16 v[22:25], v[162:165], v[218:221], v[22:25]
	v_mfma_f32_16x16x32_bf16 v[8:11], v[154:157], v[226:229], v[8:11]
	v_mfma_f32_16x16x32_bf16 v[2:5], v[162:165], v[226:229], v[2:5]
	s_setprio 0
	s_barrier
	s_add_i32 s33, 0, 0x18000
	v_add_u32_e32 v0, s33, v249
	s_add_i32 s62, 0, 0x1c000
	ds_read_b128 v[134:137], v0
	ds_read_b128 v[138:141], v0 offset:1024
	ds_read_b128 v[142:145], v0 offset:2048
	ds_read_b128 v[146:149], v0 offset:3072
	v_add_u32_e32 v0, s62, v249
	ds_read_b128 v[150:153], v0
	ds_read_b128 v[154:157], v0 offset:1024
	ds_read_b128 v[158:161], v0 offset:2048
	ds_read_b128 v[162:165], v0 offset:3072
	s_add_u32 s36, s36, 0x80000
	s_addc_u32 s37, s37, 0
	s_mov_b32 m0, s45
	v_lshl_add_u64 v[6:7], s[36:37], 0, v[206:207]
	ds_read_b128 v[176:179], v202 offset:32768
	ds_read_b128 v[180:183], v202 offset:33792
	ds_read_b128 v[184:187], v202 offset:34816
	ds_read_b128 v[188:191], v202 offset:35840
	ds_read_b128 v[192:195], v202 offset:36864
	ds_read_b128 v[218:221], v202 offset:37888
	ds_read_b128 v[222:225], v202 offset:38912
	ds_read_b128 v[226:229], v202 offset:39936
	global_load_lds_dwordx4 v206, s[36:37]
	v_lshl_add_u64 v[6:7], s[36:37], 0, v[210:211]
	s_mov_b32 m0, s46
	s_nop 0
	global_load_lds_dwordx4 v210, s[36:37]
	s_waitcnt vmcnt(8)
	s_waitcnt lgkmcnt(0)
	s_barrier
	s_setprio 1
	s_waitcnt lgkmcnt(0)
	v_mfma_f32_16x16x32_bf16 v[130:133], v[134:137], v[176:179], v[130:133]
	v_mfma_f32_16x16x32_bf16 v[130:133], v[138:141], v[180:183], v[130:133]
	v_mfma_f32_16x16x32_bf16 v[126:129], v[142:145], v[176:179], v[126:129]
	v_mfma_f32_16x16x32_bf16 v[126:129], v[146:149], v[180:183], v[126:129]
	v_mfma_f32_16x16x32_bf16 v[114:117], v[134:137], v[184:187], v[114:117]
	v_mfma_f32_16x16x32_bf16 v[114:117], v[138:141], v[188:191], v[114:117]
	v_mfma_f32_16x16x32_bf16 v[110:113], v[142:145], v[184:187], v[110:113]
	v_mfma_f32_16x16x32_bf16 v[110:113], v[146:149], v[188:191], v[110:113]
	v_mfma_f32_16x16x32_bf16 v[98:101], v[134:137], v[192:195], v[98:101]
	v_mfma_f32_16x16x32_bf16 v[98:101], v[138:141], v[218:221], v[98:101]
	v_mfma_f32_16x16x32_bf16 v[94:97], v[142:145], v[192:195], v[94:97]
	v_mfma_f32_16x16x32_bf16 v[94:97], v[146:149], v[218:221], v[94:97]
	v_mfma_f32_16x16x32_bf16 v[82:85], v[134:137], v[222:225], v[82:85]
	v_mfma_f32_16x16x32_bf16 v[82:85], v[138:141], v[226:229], v[82:85]
	v_mfma_f32_16x16x32_bf16 v[78:81], v[142:145], v[222:225], v[78:81]
	v_mfma_f32_16x16x32_bf16 v[78:81], v[146:149], v[226:229], v[78:81]
	s_setprio 0
	s_setprio 1
	v_mfma_f32_16x16x32_bf16 v[122:125], v[150:153], v[176:179], v[122:125]
	v_mfma_f32_16x16x32_bf16 v[122:125], v[154:157], v[180:183], v[122:125]
	v_mfma_f32_16x16x32_bf16 v[118:121], v[158:161], v[176:179], v[118:121]
	v_mfma_f32_16x16x32_bf16 v[118:121], v[162:165], v[180:183], v[118:121]
	v_mfma_f32_16x16x32_bf16 v[106:109], v[150:153], v[184:187], v[106:109]
	v_mfma_f32_16x16x32_bf16 v[106:109], v[154:157], v[188:191], v[106:109]
	v_mfma_f32_16x16x32_bf16 v[102:105], v[158:161], v[184:187], v[102:105]
	v_mfma_f32_16x16x32_bf16 v[102:105], v[162:165], v[188:191], v[102:105]
	v_mfma_f32_16x16x32_bf16 v[90:93], v[150:153], v[192:195], v[90:93]
	v_mfma_f32_16x16x32_bf16 v[90:93], v[154:157], v[218:221], v[90:93]
	v_mfma_f32_16x16x32_bf16 v[86:89], v[158:161], v[192:195], v[86:89]
	v_mfma_f32_16x16x32_bf16 v[86:89], v[162:165], v[218:221], v[86:89]
	v_mfma_f32_16x16x32_bf16 v[74:77], v[150:153], v[222:225], v[74:77]
	v_mfma_f32_16x16x32_bf16 v[74:77], v[154:157], v[226:229], v[74:77]
	v_mfma_f32_16x16x32_bf16 v[70:73], v[158:161], v[222:225], v[70:73]
	v_mfma_f32_16x16x32_bf16 v[70:73], v[162:165], v[226:229], v[70:73]
	s_setprio 0
	s_barrier
; #define PG8_STAGE(bufoff, gbase, voff) do { _Pragma("unroll") for (int _i = 0; _i < 2; ++_i) \
;         __builtin_amdgcn_global_load_lds((const unsigned*)((const char*)(gbase) + (voff)[_i]), (PG8_LAS unsigned*)(lds + (bufoff) + ldsw + _i * 8192), 16, 0, 0); } while (0)
; #define PG8_LDA(dst, b, h) do { _Pragma("unroll") for (int m = 0; m < 4; ++m) _Pragma("unroll") for (int k = 0; k < 2; ++k) dst[m][k] = *(const PG8_LAS bf16x8*)(lds + PG8_SA(b, h) + aoff + m * 2048 + k * 1024); } while (0)
; #define PG8_MMA(ai, bj, At, Bt) do { __builtin_amdgcn_s_setprio(1); _Pragma("unroll") for (int m = 0; m < 4; ++m) _Pragma("unroll") for (int n = 0; n < 2; ++n) _Pragma("unroll") for (int k = 0; k < 2; ++k) \
;         acc[ai][bj][m][n] = __builtin_amdgcn_mfma_f32_16x16x32_bf16(Bt[n][k], At[m][k], acc[ai][bj][m][n], 0, 0, 0); __builtin_amdgcn_s_setprio(0); } while (0)
; #define PG8_WAIT_V(n) asm volatile("s_waitcnt vmcnt(" #n ")" ::: "memory")
; #define PG8_WAIT_L(n) asm volatile("s_waitcnt lgkmcnt(" #n ")" ::: "memory")
; #define PG8_BAR __builtin_amdgcn_s_barrier()
; #define PG8_SCHED __builtin_amdgcn_sched_barrier(0)
; template <class Epi, class Sched, bool ALIGN_EPI = false, bool SP2 = false>
; __device__ __forceinline__ void gemm_phase(PG8_LAS unsigned char* lds, const Gemm g, const Sched& S, const Epi& E) {
;     ...
;             PG8_LDA(At, 1, 1); PG8_STAGE(PG8_SB(1, 0), b3, voffB); PG8_STAGE(PG8_SB(1, 1), b3 + hstep, voffB); PG8_STAGE(PG8_SA(1, 0), a3, voffA);
;             PG8_WAIT_V(8); PG8_WAIT_L(0); PG8_BAR; PG8_MMA(1, 0, At, B0); PG8_MMA(1, 1, At, B1); PG8_BAR; PG8_SCHED;
	s_add_i32 s33, s33, s43
	v_lshl_add_u64 v[6:7], v[196:197], 0, s[92:93]
	s_mov_b32 m0, s33
	ds_read_b128 v[176:179], v202 offset:49152
	ds_read_b128 v[180:183], v202 offset:50176
	ds_read_b128 v[184:187], v202 offset:51200
	ds_read_b128 v[188:191], v202 offset:52224
	ds_read_b128 v[192:195], v202 offset:53248
	ds_read_b128 v[218:221], v202 offset:54272
	ds_read_b128 v[222:225], v202 offset:55296
	ds_read_b128 v[226:229], v202 offset:56320
	global_load_lds_dwordx4 v[6:7], off
	s_add_i32 m0, s33, 0x2000
	s_add_u32 s6, s6, 0x80080
	v_lshl_add_u64 v[6:7], v[230:231], 0, s[92:93]
	s_addc_u32 s7, s7, 0
	s_add_i32 s33, s62, s43
	global_load_lds_dwordx4 v[6:7], off
	v_lshl_add_u64 v[6:7], s[6:7], 0, v[208:209]
	s_mov_b32 m0, s33
	s_nop 0
	global_load_lds_dwordx4 v208, s[6:7]
	v_lshl_add_u64 v[6:7], s[6:7], 0, v[212:213]
	s_add_i32 m0, s33, 0x2000
	s_nop 0
	global_load_lds_dwordx4 v212, s[6:7]
	v_lshl_add_u64 v[6:7], v[232:233], 0, s[92:93]
	s_mov_b32 m0, s48
	s_nop 0
	global_load_lds_dwordx4 v[6:7], off
	v_lshl_add_u64 v[6:7], v[234:235], 0, s[92:93]
	s_mov_b32 m0, s49
	s_nop 0
	global_load_lds_dwordx4 v[6:7], off
	s_waitcnt vmcnt(8)
	s_waitcnt lgkmcnt(0)
	s_barrier
	s_setprio 1
	s_waitcnt lgkmcnt(0)
	v_mfma_f32_16x16x32_bf16 v[66:69], v[134:137], v[176:179], v[66:69]
	v_mfma_f32_16x16x32_bf16 v[66:69], v[138:141], v[180:183], v[66:69]
	v_mfma_f32_16x16x32_bf16 v[62:65], v[142:145], v[176:179], v[62:65]
	v_mfma_f32_16x16x32_bf16 v[62:65], v[146:149], v[180:183], v[62:65]
	v_mfma_f32_16x16x32_bf16 v[50:53], v[134:137], v[184:187], v[50:53]
	v_mfma_f32_16x16x32_bf16 v[50:53], v[138:141], v[188:191], v[50:53]
	v_mfma_f32_16x16x32_bf16 v[46:49], v[142:145], v[184:187], v[46:49]
	v_mfma_f32_16x16x32_bf16 v[46:49], v[146:149], v[188:191], v[46:49]
	v_mfma_f32_16x16x32_bf16 v[34:37], v[134:137], v[192:195], v[34:37]
	v_mfma_f32_16x16x32_bf16 v[34:37], v[138:141], v[218:221], v[34:37]
	v_mfma_f32_16x16x32_bf16 v[30:33], v[142:145], v[192:195], v[30:33]
	v_mfma_f32_16x16x32_bf16 v[30:33], v[146:149], v[218:221], v[30:33]
	v_mfma_f32_16x16x32_bf16 v[18:21], v[134:137], v[222:225], v[18:21]
	v_mfma_f32_16x16x32_bf16 v[18:21], v[138:141], v[226:229], v[18:21]
	v_mfma_f32_16x16x32_bf16 v[12:15], v[142:145], v[222:225], v[12:15]
	v_mfma_f32_16x16x32_bf16 v[12:15], v[146:149], v[226:229], v[12:15]
	s_setprio 0
	s_setprio 1
	v_mfma_f32_16x16x32_bf16 v[58:61], v[150:153], v[176:179], v[58:61]
	v_mfma_f32_16x16x32_bf16 v[54:57], v[158:161], v[176:179], v[54:57]
	v_mfma_f32_16x16x32_bf16 v[42:45], v[150:153], v[184:187], v[42:45]
	v_mfma_f32_16x16x32_bf16 v[38:41], v[158:161], v[184:187], v[38:41]
	v_mfma_f32_16x16x32_bf16 v[26:29], v[150:153], v[192:195], v[26:29]
	v_mfma_f32_16x16x32_bf16 v[22:25], v[158:161], v[192:195], v[22:25]
	v_mfma_f32_16x16x32_bf16 v[6:9], v[150:153], v[222:225], v[8:11]
	v_mfma_f32_16x16x32_bf16 v[2:5], v[158:161], v[222:225], v[2:5]
	v_mfma_f32_16x16x32_bf16 v[58:61], v[154:157], v[180:183], v[58:61]
	v_mfma_f32_16x16x32_bf16 v[54:57], v[162:165], v[180:183], v[54:57]
	v_mfma_f32_16x16x32_bf16 v[42:45], v[154:157], v[188:191], v[42:45]
	v_mfma_f32_16x16x32_bf16 v[38:41], v[162:165], v[188:191], v[38:41]
	v_mfma_f32_16x16x32_bf16 v[26:29], v[154:157], v[218:221], v[26:29]
	v_mfma_f32_16x16x32_bf16 v[22:25], v[162:165], v[218:221], v[22:25]
	v_mfma_f32_16x16x32_bf16 v[8:11], v[154:157], v[226:229], v[6:9]
	v_mfma_f32_16x16x32_bf16 v[4:7], v[162:165], v[226:229], v[2:5]
	s_setprio 0
	s_barrier
	s_add_i32 s61, s61, 2
	s_add_u32 s34, s34, 0x100
	s_addc_u32 s35, s35, 0
	s_cmp_gt_u32 s61, 29
	s_cbranch_scc1 .LBB0_1096

; #define PG8_STAGE(bufoff, gbase, voff) do { _Pragma("unroll") for (int _i = 0; _i < 2; ++_i) \
;         __builtin_amdgcn_global_load_lds((const unsigned*)((const char*)(gbase) + (voff)[_i]), (PG8_LAS unsigned*)(lds + (bufoff) + ldsw + _i * 8192), 16, 0, 0); } while (0)
; #define PG8_LDA(dst, b, h) do { _Pragma("unroll") for (int m = 0; m < 4; ++m) _Pragma("unroll") for (int k = 0; k < 2; ++k) dst[m][k] = *(const PG8_LAS bf16x8*)(lds + PG8_SA(b, h) + aoff + m * 2048 + k * 1024); } while (0)
; #define PG8_LDB(dst, b, h) do { _Pragma("unroll") for (int n = 0; n < 2; ++n) _Pragma("unroll") for (int k = 0; k < 2; ++k) dst[n][k] = *(const PG8_LAS bf16x8*)(lds + PG8_SB(b, h) + boff + n * 2048 + k * 1024); } while (0)
; #define PG8_MMA(ai, bj, At, Bt) do { __builtin_amdgcn_s_setprio(1); _Pragma("unroll") for (int m = 0; m < 4; ++m) _Pragma("unroll") for (int n = 0; n < 2; ++n) _Pragma("unroll") for (int k = 0; k < 2; ++k) \
;         acc[ai][bj][m][n] = __builtin_amdgcn_mfma_f32_16x16x32_bf16(Bt[n][k], At[m][k], acc[ai][bj][m][n], 0, 0, 0); __builtin_amdgcn_s_setprio(0); } while (0)
; #define PG8_WAIT_V(n) asm volatile("s_waitcnt vmcnt(" #n ")" ::: "memory")
; #define PG8_WAIT_L(n) asm volatile("s_waitcnt lgkmcnt(" #n ")" ::: "memory")
; #define PG8_BAR __builtin_amdgcn_s_barrier()
; template <class Epi, class Sched, bool ALIGN_EPI = false, bool SP2 = false>
; __device__ __forceinline__ void gemm_phase(PG8_LAS unsigned char* lds, const Gemm g, const Sched& S, const Epi& E) {
;     ...
;             const bool last = (t == nt - 2);
;             const char* a1 = cA + (size_t)(t + 1) * kstep;
;             const char* a2 = last ? nA : cA + (size_t)(t + 2) * kstep; const char* b2 = last ? nB : cB + (size_t)(t + 2) * kstep;
;             const char* a3 = a2 + kstep; const char* b3 = b2 + kstep;
;             if (last && has_next) S.a_ready(nxt);
;             if constexpr (Epi::MID) { if (t == nt / 2) E.mid(acc, cur, wr, wc, fr, fq); }
;             if constexpr (SP2) {
;             PG8_LDB(B0, 0, 0); PG8_LDB(B1, 0, 1); PG8_SCHED; PG8_LDA(At, 0, 0); PG8_STAGE(PG8_SA(1, 1), a1 + hstep, voffA);
;             PG8_WAIT_V(8); PG8_WAIT_L(0); PG8_BAR; PG8_MMA(0, 0, At, B0); PG8_MMA(0, 1, At, B1); PG8_BAR; PG8_SCHED;
;             PG8_LDA(At, 0, 1); PG8_STAGE(PG8_SB(0, 0), b2, voffB); PG8_STAGE(PG8_SB(0, 1), b2 + hstep, voffB); PG8_STAGE(PG8_SA(0, 0), a2, voffA);
.LBB0_1223:
	s_add_u32 s28, s26, 0xfff80080
	s_addc_u32 s29, s27, -1
	s_add_i32 s33, 0, 0x10000
	s_cmp_eq_u32 s56, 28
	s_cselect_b32 s31, s5, s29
	s_cselect_b32 s30, s11, s28
	v_add_u32_e32 v161, s33, v155
	s_cselect_b32 s29, s19, s55
	s_cselect_b32 s28, s21, s54
	s_add_i32 s57, 0, 0x14000
	ds_read_b128 v[142:145], v161
	ds_read_b128 v[146:149], v161 offset:1024
	ds_read_b128 v[150:153], v161 offset:2048
	ds_read_b128 v[162:165], v161 offset:3072
	v_add_u32_e32 v161, s57, v155
	ds_read_b128 v[166:169], v161
	ds_read_b128 v[170:173], v161 offset:1024
	ds_read_b128 v[174:177], v161 offset:2048
	ds_read_b128 v[178:181], v161 offset:3072
	v_lshl_add_u64 v[202:203], s[26:27], 0, v[140:141]
	s_add_i32 m0, s42, 0xc000
	ds_read_b128 v[182:185], v160
	ds_read_b128 v[186:189], v160 offset:1024
	ds_read_b128 v[190:193], v160 offset:2048
	ds_read_b128 v[194:197], v160 offset:3072
	ds_read_b128 v[198:201], v160 offset:4096
	ds_read_b128 v[206:209], v160 offset:5120
	ds_read_b128 v[210:213], v160 offset:6144
	ds_read_b128 v[214:217], v160 offset:7168
	global_load_lds_dwordx4 v140, s[26:27]
	v_lshl_add_u64 v[202:203], s[26:27], 0, v[138:139]
	s_add_i32 m0, s42, 0xe000
	s_nop 0
	global_load_lds_dwordx4 v138, s[26:27]
	s_waitcnt vmcnt(8)
	s_waitcnt lgkmcnt(0)
	s_barrier
	s_setprio 1
	s_waitcnt lgkmcnt(0)
	v_mfma_f32_16x16x32_bf16 v[130:133], v[142:145], v[182:185], v[130:133]
	v_mfma_f32_16x16x32_bf16 v[130:133], v[146:149], v[186:189], v[130:133]
	v_mfma_f32_16x16x32_bf16 v[126:129], v[150:153], v[182:185], v[126:129]
	v_mfma_f32_16x16x32_bf16 v[126:129], v[162:165], v[186:189], v[126:129]
	v_mfma_f32_16x16x32_bf16 v[114:117], v[142:145], v[190:193], v[114:117]
	v_mfma_f32_16x16x32_bf16 v[114:117], v[146:149], v[194:197], v[114:117]
	v_mfma_f32_16x16x32_bf16 v[110:113], v[150:153], v[190:193], v[110:113]
	v_mfma_f32_16x16x32_bf16 v[110:113], v[162:165], v[194:197], v[110:113]
	v_mfma_f32_16x16x32_bf16 v[98:101], v[142:145], v[198:201], v[98:101]
	v_mfma_f32_16x16x32_bf16 v[98:101], v[146:149], v[206:209], v[98:101]
	v_mfma_f32_16x16x32_bf16 v[94:97], v[150:153], v[198:201], v[94:97]
	v_mfma_f32_16x16x32_bf16 v[94:97], v[162:165], v[206:209], v[94:97]
	v_mfma_f32_16x16x32_bf16 v[82:85], v[142:145], v[210:213], v[82:85]
	v_mfma_f32_16x16x32_bf16 v[82:85], v[146:149], v[214:217], v[82:85]
	v_mfma_f32_16x16x32_bf16 v[78:81], v[150:153], v[210:213], v[78:81]
	v_mfma_f32_16x16x32_bf16 v[78:81], v[162:165], v[214:217], v[78:81]
	s_setprio 0
	s_setprio 1
	v_mfma_f32_16x16x32_bf16 v[122:125], v[166:169], v[182:185], v[122:125]
	v_mfma_f32_16x16x32_bf16 v[122:125], v[170:173], v[186:189], v[122:125]
	v_mfma_f32_16x16x32_bf16 v[118:121], v[174:177], v[182:185], v[118:121]
	v_mfma_f32_16x16x32_bf16 v[118:121], v[178:181], v[186:189], v[118:121]
	v_mfma_f32_16x16x32_bf16 v[106:109], v[166:169], v[190:193], v[106:109]
	v_mfma_f32_16x16x32_bf16 v[106:109], v[170:173], v[194:197], v[106:109]
	v_mfma_f32_16x16x32_bf16 v[102:105], v[174:177], v[190:193], v[102:105]
	v_mfma_f32_16x16x32_bf16 v[102:105], v[178:181], v[194:197], v[102:105]
	v_mfma_f32_16x16x32_bf16 v[90:93], v[166:169], v[198:201], v[90:93]
	v_mfma_f32_16x16x32_bf16 v[90:93], v[170:173], v[206:209], v[90:93]
	v_mfma_f32_16x16x32_bf16 v[86:89], v[174:177], v[198:201], v[86:89]
	v_mfma_f32_16x16x32_bf16 v[86:89], v[178:181], v[206:209], v[86:89]
	v_mfma_f32_16x16x32_bf16 v[74:77], v[166:169], v[210:213], v[74:77]
	v_mfma_f32_16x16x32_bf16 v[74:77], v[170:173], v[214:217], v[74:77]
	v_mfma_f32_16x16x32_bf16 v[70:73], v[174:177], v[210:213], v[70:73]
	v_mfma_f32_16x16x32_bf16 v[70:73], v[178:181], v[214:217], v[70:73]
	s_setprio 0
	s_barrier
	s_add_i32 s33, s33, s40
	v_lshl_add_u64 v[202:203], s[28:29], 0, v[0:1]
	s_mov_b32 m0, s33
	ds_read_b128 v[182:185], v160 offset:16384
	ds_read_b128 v[186:189], v160 offset:17408
	ds_read_b128 v[190:193], v160 offset:18432
	ds_read_b128 v[194:197], v160 offset:19456
	ds_read_b128 v[198:201], v160 offset:20480
	ds_read_b128 v[206:209], v160 offset:21504
	ds_read_b128 v[210:213], v160 offset:22528
	ds_read_b128 v[214:217], v160 offset:23552
	global_load_lds_dwordx4 v0, s[28:29]
	s_add_i32 m0, s33, 0x2000
	s_add_u32 s58, s28, 0x80000
	v_lshl_add_u64 v[218:219], s[28:29], 0, v[14:15]
	s_addc_u32 s59, s29, 0
	s_add_i32 s33, s57, s40
	global_load_lds_dwordx4 v14, s[28:29]
	v_lshl_add_u64 v[220:221], s[58:59], 0, v[0:1]
	s_mov_b32 m0, s33
	v_lshl_add_u64 v[222:223], s[30:31], 0, v[134:135]
	global_load_lds_dwordx4 v0, s[58:59]
	v_lshl_add_u64 v[220:221], s[58:59], 0, v[14:15]
	s_add_i32 m0, s33, 0x2000
	s_nop 0
	global_load_lds_dwordx4 v14, s[58:59]
	v_lshl_add_u64 v[220:221], s[30:31], 0, v[136:137]
	s_mov_b32 m0, s42
	s_nop 0
	global_load_lds_dwordx4 v136, s[30:31]
	s_mov_b32 m0, s43
	s_nop 0
	global_load_lds_dwordx4 v134, s[30:31]
	s_waitcnt vmcnt(8)
	s_waitcnt lgkmcnt(0)
	s_barrier
; #define PG8_STAGE(bufoff, gbase, voff) do { _Pragma("unroll") for (int _i = 0; _i < 2; ++_i) \
;         __builtin_amdgcn_global_load_lds((const unsigned*)((const char*)(gbase) + (voff)[_i]), (PG8_LAS unsigned*)(lds + (bufoff) + ldsw + _i * 8192), 16, 0, 0); } while (0)
; #define PG8_LDA(dst, b, h) do { _Pragma("unroll") for (int m = 0; m < 4; ++m) _Pragma("unroll") for (int k = 0; k < 2; ++k) dst[m][k] = *(const PG8_LAS bf16x8*)(lds + PG8_SA(b, h) + aoff + m * 2048 + k * 1024); } while (0)
; #define PG8_LDB(dst, b, h) do { _Pragma("unroll") for (int n = 0; n < 2; ++n) _Pragma("unroll") for (int k = 0; k < 2; ++k) dst[n][k] = *(const PG8_LAS bf16x8*)(lds + PG8_SB(b, h) + boff + n * 2048 + k * 1024); } while (0)
; #define PG8_MMA(ai, bj, At, Bt) do { __builtin_amdgcn_s_setprio(1); _Pragma("unroll") for (int m = 0; m < 4; ++m) _Pragma("unroll") for (int n = 0; n < 2; ++n) _Pragma("unroll") for (int k = 0; k < 2; ++k) \
;         acc[ai][bj][m][n] = __builtin_amdgcn_mfma_f32_16x16x32_bf16(Bt[n][k], At[m][k], acc[ai][bj][m][n], 0, 0, 0); __builtin_amdgcn_s_setprio(0); } while (0)
; #define PG8_WAIT_V(n) asm volatile("s_waitcnt vmcnt(" #n ")" ::: "memory")
; #define PG8_WAIT_L(n) asm volatile("s_waitcnt lgkmcnt(" #n ")" ::: "memory")
; #define PG8_BAR __builtin_amdgcn_s_barrier()
; #define PG8_SCHED __builtin_amdgcn_sched_barrier(0)
; template <class Epi, class Sched, bool ALIGN_EPI = false, bool SP2 = false>
; __device__ __forceinline__ void gemm_phase(PG8_LAS unsigned char* lds, const Gemm g, const Sched& S, const Epi& E) {
;     ...
;             PG8_WAIT_V(8); PG8_WAIT_L(0); PG8_BAR; PG8_MMA(1, 0, At, B0); PG8_MMA(1, 1, At, B1); PG8_BAR; PG8_SCHED;
;             PG8_LDB(B0, 1, 0); PG8_LDB(B1, 1, 1); PG8_SCHED; PG8_LDA(At, 1, 0); PG8_STAGE(PG8_SA(0, 1), a2 + hstep, voffA);
;             PG8_WAIT_V(8); PG8_WAIT_L(0); PG8_BAR; PG8_MMA(0, 0, At, B0); PG8_MMA(0, 1, At, B1); PG8_BAR; PG8_SCHED;
	s_setprio 1
	s_waitcnt lgkmcnt(0)
	v_mfma_f32_16x16x32_bf16 v[66:69], v[142:145], v[182:185], v[66:69]
	v_mfma_f32_16x16x32_bf16 v[66:69], v[146:149], v[186:189], v[66:69]
	v_mfma_f32_16x16x32_bf16 v[62:65], v[150:153], v[182:185], v[62:65]
	v_mfma_f32_16x16x32_bf16 v[62:65], v[162:165], v[186:189], v[62:65]
	v_mfma_f32_16x16x32_bf16 v[50:53], v[142:145], v[190:193], v[50:53]
	v_mfma_f32_16x16x32_bf16 v[50:53], v[146:149], v[194:197], v[50:53]
	v_mfma_f32_16x16x32_bf16 v[46:49], v[150:153], v[190:193], v[46:49]
	v_mfma_f32_16x16x32_bf16 v[46:49], v[162:165], v[194:197], v[46:49]
	v_mfma_f32_16x16x32_bf16 v[34:37], v[142:145], v[198:201], v[34:37]
	v_mfma_f32_16x16x32_bf16 v[34:37], v[146:149], v[206:209], v[34:37]
	v_mfma_f32_16x16x32_bf16 v[30:33], v[150:153], v[198:201], v[30:33]
	v_mfma_f32_16x16x32_bf16 v[30:33], v[162:165], v[206:209], v[30:33]
	v_mfma_f32_16x16x32_bf16 v[18:21], v[142:145], v[210:213], v[18:21]
	v_mfma_f32_16x16x32_bf16 v[18:21], v[146:149], v[214:217], v[18:21]
	v_mfma_f32_16x16x32_bf16 v[10:13], v[150:153], v[210:213], v[10:13]
	v_mfma_f32_16x16x32_bf16 v[10:13], v[162:165], v[214:217], v[10:13]
	s_setprio 0
	s_setprio 1
	v_mfma_f32_16x16x32_bf16 v[58:61], v[166:169], v[182:185], v[58:61]
	v_mfma_f32_16x16x32_bf16 v[58:61], v[170:173], v[186:189], v[58:61]
	v_mfma_f32_16x16x32_bf16 v[54:57], v[174:177], v[182:185], v[54:57]
	v_mfma_f32_16x16x32_bf16 v[54:57], v[178:181], v[186:189], v[54:57]
	v_mfma_f32_16x16x32_bf16 v[42:45], v[166:169], v[190:193], v[42:45]
	v_mfma_f32_16x16x32_bf16 v[42:45], v[170:173], v[194:197], v[42:45]
	v_mfma_f32_16x16x32_bf16 v[38:41], v[174:177], v[190:193], v[38:41]
	v_mfma_f32_16x16x32_bf16 v[38:41], v[178:181], v[194:197], v[38:41]
	v_mfma_f32_16x16x32_bf16 v[26:29], v[166:169], v[198:201], v[26:29]
	v_mfma_f32_16x16x32_bf16 v[26:29], v[170:173], v[206:209], v[26:29]
	v_mfma_f32_16x16x32_bf16 v[22:25], v[174:177], v[198:201], v[22:25]
	v_mfma_f32_16x16x32_bf16 v[22:25], v[178:181], v[206:209], v[22:25]
	v_mfma_f32_16x16x32_bf16 v[6:9], v[166:169], v[210:213], v[6:9]
	v_mfma_f32_16x16x32_bf16 v[6:9], v[170:173], v[214:217], v[6:9]
	v_mfma_f32_16x16x32_bf16 v[2:5], v[174:177], v[210:213], v[2:5]
	v_mfma_f32_16x16x32_bf16 v[2:5], v[178:181], v[214:217], v[2:5]
	s_setprio 0
	s_barrier
	s_add_i32 s33, 0, 0x18000
	v_add_u32_e32 v161, s33, v155
	s_add_i32 s57, 0, 0x1c000
	ds_read_b128 v[142:145], v161
	ds_read_b128 v[146:149], v161 offset:1024
	ds_read_b128 v[150:153], v161 offset:2048
	ds_read_b128 v[162:165], v161 offset:3072
	v_add_u32_e32 v161, s57, v155
	ds_read_b128 v[166:169], v161
	ds_read_b128 v[170:173], v161 offset:1024
	ds_read_b128 v[174:177], v161 offset:2048
	ds_read_b128 v[178:181], v161 offset:3072
	s_add_u32 s30, s30, 0x80000
	s_addc_u32 s31, s31, 0
	s_mov_b32 m0, s44
	v_lshl_add_u64 v[224:225], s[30:31], 0, v[136:137]
	ds_read_b128 v[182:185], v160 offset:32768
	ds_read_b128 v[186:189], v160 offset:33792
	ds_read_b128 v[190:193], v160 offset:34816
	ds_read_b128 v[194:197], v160 offset:35840
	ds_read_b128 v[198:201], v160 offset:36864
	ds_read_b128 v[206:209], v160 offset:37888
	ds_read_b128 v[210:213], v160 offset:38912
	ds_read_b128 v[214:217], v160 offset:39936
	global_load_lds_dwordx4 v136, s[30:31]
	v_lshl_add_u64 v[224:225], s[30:31], 0, v[134:135]
	s_mov_b32 m0, s45
	s_nop 0
	global_load_lds_dwordx4 v134, s[30:31]
	s_waitcnt vmcnt(8)
	s_waitcnt lgkmcnt(0)
	s_barrier
	s_setprio 1
	s_waitcnt lgkmcnt(0)
	v_mfma_f32_16x16x32_bf16 v[130:133], v[142:145], v[182:185], v[130:133]
	v_mfma_f32_16x16x32_bf16 v[130:133], v[146:149], v[186:189], v[130:133]
	v_mfma_f32_16x16x32_bf16 v[126:129], v[150:153], v[182:185], v[126:129]
	v_mfma_f32_16x16x32_bf16 v[126:129], v[162:165], v[186:189], v[126:129]
	v_mfma_f32_16x16x32_bf16 v[114:117], v[142:145], v[190:193], v[114:117]
	v_mfma_f32_16x16x32_bf16 v[114:117], v[146:149], v[194:197], v[114:117]
	v_mfma_f32_16x16x32_bf16 v[110:113], v[150:153], v[190:193], v[110:113]
	v_mfma_f32_16x16x32_bf16 v[110:113], v[162:165], v[194:197], v[110:113]
	v_mfma_f32_16x16x32_bf16 v[98:101], v[142:145], v[198:201], v[98:101]
	v_mfma_f32_16x16x32_bf16 v[98:101], v[146:149], v[206:209], v[98:101]
	v_mfma_f32_16x16x32_bf16 v[94:97], v[150:153], v[198:201], v[94:97]
	v_mfma_f32_16x16x32_bf16 v[94:97], v[162:165], v[206:209], v[94:97]
	v_mfma_f32_16x16x32_bf16 v[82:85], v[142:145], v[210:213], v[82:85]
	v_mfma_f32_16x16x32_bf16 v[82:85], v[146:149], v[214:217], v[82:85]
	v_mfma_f32_16x16x32_bf16 v[78:81], v[150:153], v[210:213], v[78:81]
	v_mfma_f32_16x16x32_bf16 v[78:81], v[162:165], v[214:217], v[78:81]
	s_setprio 0
	s_setprio 1
	v_mfma_f32_16x16x32_bf16 v[122:125], v[166:169], v[182:185], v[122:125]
	v_mfma_f32_16x16x32_bf16 v[122:125], v[170:173], v[186:189], v[122:125]
	v_mfma_f32_16x16x32_bf16 v[118:121], v[174:177], v[182:185], v[118:121]
	v_mfma_f32_16x16x32_bf16 v[118:121], v[178:181], v[186:189], v[118:121]
	v_mfma_f32_16x16x32_bf16 v[106:109], v[166:169], v[190:193], v[106:109]
	v_mfma_f32_16x16x32_bf16 v[106:109], v[170:173], v[194:197], v[106:109]
	v_mfma_f32_16x16x32_bf16 v[102:105], v[174:177], v[190:193], v[102:105]
	v_mfma_f32_16x16x32_bf16 v[102:105], v[178:181], v[194:197], v[102:105]
	v_mfma_f32_16x16x32_bf16 v[90:93], v[166:169], v[198:201], v[90:93]
	v_mfma_f32_16x16x32_bf16 v[90:93], v[170:173], v[206:209], v[90:93]
	v_mfma_f32_16x16x32_bf16 v[86:89], v[174:177], v[198:201], v[86:89]
	v_mfma_f32_16x16x32_bf16 v[86:89], v[178:181], v[206:209], v[86:89]
	v_mfma_f32_16x16x32_bf16 v[74:77], v[166:169], v[210:213], v[74:77]
	v_mfma_f32_16x16x32_bf16 v[74:77], v[170:173], v[214:217], v[74:77]
	v_mfma_f32_16x16x32_bf16 v[70:73], v[174:177], v[210:213], v[70:73]
	v_mfma_f32_16x16x32_bf16 v[70:73], v[178:181], v[214:217], v[70:73]
	s_setprio 0
	s_barrier
; #define PG8_STAGE(bufoff, gbase, voff) do { _Pragma("unroll") for (int _i = 0; _i < 2; ++_i) \
;         __builtin_amdgcn_global_load_lds((const unsigned*)((const char*)(gbase) + (voff)[_i]), (PG8_LAS unsigned*)(lds + (bufoff) + ldsw + _i * 8192), 16, 0, 0); } while (0)
; #define PG8_LDA(dst, b, h) do { _Pragma("unroll") for (int m = 0; m < 4; ++m) _Pragma("unroll") for (int k = 0; k < 2; ++k) dst[m][k] = *(const PG8_LAS bf16x8*)(lds + PG8_SA(b, h) + aoff + m * 2048 + k * 1024); } while (0)
; #define PG8_MMA(ai, bj, At, Bt) do { __builtin_amdgcn_s_setprio(1); _Pragma("unroll") for (int m = 0; m < 4; ++m) _Pragma("unroll") for (int n = 0; n < 2; ++n) _Pragma("unroll") for (int k = 0; k < 2; ++k) \
;         acc[ai][bj][m][n] = __builtin_amdgcn_mfma_f32_16x16x32_bf16(Bt[n][k], At[m][k], acc[ai][bj][m][n], 0, 0, 0); __builtin_amdgcn_s_setprio(0); } while (0)
; #define PG8_WAIT_V(n) asm volatile("s_waitcnt vmcnt(" #n ")" ::: "memory")
; #define PG8_WAIT_L(n) asm volatile("s_waitcnt lgkmcnt(" #n ")" ::: "memory")
; #define PG8_BAR __builtin_amdgcn_s_barrier()
; #define PG8_SCHED __builtin_amdgcn_sched_barrier(0)
; template <class Epi, class Sched, bool ALIGN_EPI = false, bool SP2 = false>
; __device__ __forceinline__ void gemm_phase(PG8_LAS unsigned char* lds, const Gemm g, const Sched& S, const Epi& E) {
;     ...
;             PG8_LDA(At, 1, 1); PG8_STAGE(PG8_SB(1, 0), b3, voffB); PG8_STAGE(PG8_SB(1, 1), b3 + hstep, voffB); PG8_STAGE(PG8_SA(1, 0), a3, voffA);
;             PG8_WAIT_V(8); PG8_WAIT_L(0); PG8_BAR; PG8_MMA(1, 0, At, B0); PG8_MMA(1, 1, At, B1); PG8_BAR; PG8_SCHED;
	s_add_i32 s30, s33, s40
	v_lshl_add_u64 v[202:203], v[202:203], 0, s[92:93]
	s_mov_b32 m0, s30
	ds_read_b128 v[182:185], v160 offset:49152
	ds_read_b128 v[186:189], v160 offset:50176
	ds_read_b128 v[190:193], v160 offset:51200
	ds_read_b128 v[194:197], v160 offset:52224
	ds_read_b128 v[198:201], v160 offset:53248
	ds_read_b128 v[206:209], v160 offset:54272
	ds_read_b128 v[210:213], v160 offset:55296
	ds_read_b128 v[214:217], v160 offset:56320
	global_load_lds_dwordx4 v[202:203], off
	s_add_i32 m0, s30, 0x2000
	s_add_u32 s28, s28, 0x80080
	v_lshl_add_u64 v[202:203], v[218:219], 0, s[92:93]
	s_addc_u32 s29, s29, 0
	s_add_i32 s30, s57, s40
	global_load_lds_dwordx4 v[202:203], off
	v_lshl_add_u64 v[202:203], s[28:29], 0, v[0:1]
	s_mov_b32 m0, s30
	s_nop 0
	global_load_lds_dwordx4 v0, s[28:29]
	v_lshl_add_u64 v[202:203], s[28:29], 0, v[14:15]
	s_add_i32 m0, s30, 0x2000
	s_nop 0
	global_load_lds_dwordx4 v14, s[28:29]
	v_lshl_add_u64 v[202:203], v[220:221], 0, s[92:93]
	s_mov_b32 m0, s47
	s_nop 0
	global_load_lds_dwordx4 v[202:203], off
	v_lshl_add_u64 v[202:203], v[222:223], 0, s[92:93]
	s_mov_b32 m0, s48
	s_nop 0
	global_load_lds_dwordx4 v[202:203], off
	s_waitcnt vmcnt(8)
	s_waitcnt lgkmcnt(0)
	s_barrier
	s_setprio 1
	s_waitcnt lgkmcnt(0)
	v_mfma_f32_16x16x32_bf16 v[66:69], v[142:145], v[182:185], v[66:69]
	v_mfma_f32_16x16x32_bf16 v[66:69], v[146:149], v[186:189], v[66:69]
	v_mfma_f32_16x16x32_bf16 v[62:65], v[150:153], v[182:185], v[62:65]
	v_mfma_f32_16x16x32_bf16 v[62:65], v[162:165], v[186:189], v[62:65]
	v_mfma_f32_16x16x32_bf16 v[50:53], v[142:145], v[190:193], v[50:53]
	v_mfma_f32_16x16x32_bf16 v[50:53], v[146:149], v[194:197], v[50:53]
	v_mfma_f32_16x16x32_bf16 v[46:49], v[150:153], v[190:193], v[46:49]
	v_mfma_f32_16x16x32_bf16 v[46:49], v[162:165], v[194:197], v[46:49]
	v_mfma_f32_16x16x32_bf16 v[34:37], v[142:145], v[198:201], v[34:37]
	v_mfma_f32_16x16x32_bf16 v[34:37], v[146:149], v[206:209], v[34:37]
	v_mfma_f32_16x16x32_bf16 v[30:33], v[150:153], v[198:201], v[30:33]
	v_mfma_f32_16x16x32_bf16 v[30:33], v[162:165], v[206:209], v[30:33]
	v_mfma_f32_16x16x32_bf16 v[18:21], v[142:145], v[210:213], v[18:21]
	v_mfma_f32_16x16x32_bf16 v[18:21], v[146:149], v[214:217], v[18:21]
	v_mfma_f32_16x16x32_bf16 v[10:13], v[150:153], v[210:213], v[10:13]
	v_mfma_f32_16x16x32_bf16 v[10:13], v[162:165], v[214:217], v[10:13]
	s_setprio 0
	s_setprio 1
	v_mfma_f32_16x16x32_bf16 v[58:61], v[166:169], v[182:185], v[58:61]
	v_mfma_f32_16x16x32_bf16 v[58:61], v[170:173], v[186:189], v[58:61]
	v_mfma_f32_16x16x32_bf16 v[54:57], v[174:177], v[182:185], v[54:57]
	v_mfma_f32_16x16x32_bf16 v[54:57], v[178:181], v[186:189], v[54:57]
	v_mfma_f32_16x16x32_bf16 v[42:45], v[166:169], v[190:193], v[42:45]
	v_mfma_f32_16x16x32_bf16 v[42:45], v[170:173], v[194:197], v[42:45]
	v_mfma_f32_16x16x32_bf16 v[38:41], v[174:177], v[190:193], v[38:41]
	v_mfma_f32_16x16x32_bf16 v[38:41], v[178:181], v[194:197], v[38:41]
	v_mfma_f32_16x16x32_bf16 v[26:29], v[166:169], v[198:201], v[26:29]
	v_mfma_f32_16x16x32_bf16 v[26:29], v[170:173], v[206:209], v[26:29]
	v_mfma_f32_16x16x32_bf16 v[22:25], v[174:177], v[198:201], v[22:25]
	v_mfma_f32_16x16x32_bf16 v[22:25], v[178:181], v[206:209], v[22:25]
	v_mfma_f32_16x16x32_bf16 v[6:9], v[166:169], v[210:213], v[6:9]
	v_mfma_f32_16x16x32_bf16 v[6:9], v[170:173], v[214:217], v[6:9]
	v_mfma_f32_16x16x32_bf16 v[2:5], v[174:177], v[210:213], v[2:5]
	v_mfma_f32_16x16x32_bf16 v[2:5], v[178:181], v[214:217], v[2:5]
	s_setprio 0
	s_barrier
	s_add_i32 s56, s56, 2
	s_add_u32 s54, s54, 0x100
	s_addc_u32 s55, s55, 0
	s_add_u32 s26, s26, 0x100
	s_addc_u32 s27, s27, 0
	s_cmp_gt_u32 s56, 29
	s_cbranch_scc0 .LBB0_1223
	s_and_b64 vcc, exec, s[14:15]
	s_cbranch_vccz .LBB0_1226
	s_barrier

; #define PG8_STAGE(bufoff, gbase, voff) do { _Pragma("unroll") for (int _i = 0; _i < 2; ++_i) \
;         __builtin_amdgcn_global_load_lds((const unsigned*)((const char*)(gbase) + (voff)[_i]), (PG8_LAS unsigned*)(lds + (bufoff) + ldsw + _i * 8192), 16, 0, 0); } while (0)
; #define PG8_LDA(dst, b, h) do { _Pragma("unroll") for (int m = 0; m < 4; ++m) _Pragma("unroll") for (int k = 0; k < 2; ++k) dst[m][k] = *(const PG8_LAS bf16x8*)(lds + PG8_SA(b, h) + aoff + m * 2048 + k * 1024); } while (0)
; #define PG8_LDB(dst, b, h) do { _Pragma("unroll") for (int n = 0; n < 2; ++n) _Pragma("unroll") for (int k = 0; k < 2; ++k) dst[n][k] = *(const PG8_LAS bf16x8*)(lds + PG8_SB(b, h) + boff + n * 2048 + k * 1024); } while (0)
; #define PG8_MMA(ai, bj, At, Bt) do { __builtin_amdgcn_s_setprio(1); _Pragma("unroll") for (int m = 0; m < 4; ++m) _Pragma("unroll") for (int n = 0; n < 2; ++n) _Pragma("unroll") for (int k = 0; k < 2; ++k) \
;         acc[ai][bj][m][n] = __builtin_amdgcn_mfma_f32_16x16x32_bf16(Bt[n][k], At[m][k], acc[ai][bj][m][n], 0, 0, 0); __builtin_amdgcn_s_setprio(0); } while (0)
; #define PG8_WAIT_V(n) asm volatile("s_waitcnt vmcnt(" #n ")" ::: "memory")
; #define PG8_WAIT_L(n) asm volatile("s_waitcnt lgkmcnt(" #n ")" ::: "memory")
; #define PG8_BAR __builtin_amdgcn_s_barrier()
; template <class Epi, class Sched, bool ALIGN_EPI = false, bool SP2 = false>
; __device__ __forceinline__ void gemm_phase(PG8_LAS unsigned char* lds, const Gemm g, const Sched& S, const Epi& E) {
;     ...
;             const bool last = (t == nt - 2);
;             const char* a1 = cA + (size_t)(t + 1) * kstep;
;             const char* a2 = last ? nA : cA + (size_t)(t + 2) * kstep; const char* b2 = last ? nB : cB + (size_t)(t + 2) * kstep;
;             const char* a3 = a2 + kstep; const char* b3 = b2 + kstep;
;             if (last && has_next) S.a_ready(nxt);
;             if constexpr (Epi::MID) { if (t == nt / 2) E.mid(acc, cur, wr, wc, fr, fq); }
;             if constexpr (SP2) {
;             PG8_LDB(B0, 0, 0); PG8_LDB(B1, 0, 1); PG8_SCHED; PG8_LDA(At, 0, 0); PG8_STAGE(PG8_SA(1, 1), a1 + hstep, voffA);
;             PG8_WAIT_V(8); PG8_WAIT_L(0); PG8_BAR; PG8_MMA(0, 0, At, B0); PG8_MMA(0, 1, At, B1); PG8_BAR; PG8_SCHED;
;             PG8_LDA(At, 0, 1); PG8_STAGE(PG8_SB(0, 0), b2, voffB); PG8_STAGE(PG8_SB(0, 1), b2 + hstep, voffB); PG8_STAGE(PG8_SA(0, 0), a2, voffA);
.LBB0_1329:
	s_add_u32 s4, s24, 0x100
	s_addc_u32 s5, s25, 0
	s_add_i32 s33, 0, 0x10000
	s_cmpk_eq_i32 s53, 0x54
	s_cselect_b32 s29, s21, s5
	s_cselect_b32 s28, s20, s4
	s_cselect_b32 s27, s23, s52
	s_cselect_b32 s26, s22, s51
	s_add_i32 s54, 0, 0x14000
	v_add_u32_e32 v98, s33, v199
	v_add_u32_e32 v146, s54, v199
	ds_read_b128 v[70:73], v98
	ds_read_b128 v[74:77], v98 offset:1024
	ds_read_b128 v[86:89], v98 offset:2048
	ds_read_b128 v[98:101], v98 offset:3072
	ds_read_b128 v[110:113], v146
	ds_read_b128 v[122:125], v146 offset:1024
	ds_read_b128 v[134:137], v146 offset:2048
	ds_read_b128 v[146:149], v146 offset:3072
	v_lshl_add_u64 v[202:203], s[24:25], 0, v[208:209]
	s_add_i32 m0, s39, 0xc000
	ds_read_b128 v[158:161], v201
	ds_read_b128 v[162:165], v201 offset:1024
	ds_read_b128 v[174:177], v201 offset:2048
	ds_read_b128 v[178:181], v201 offset:3072
	ds_read_b128 v[182:185], v201 offset:4096
	ds_read_b128 v[186:189], v201 offset:5120
	ds_read_b128 v[190:193], v201 offset:6144
	ds_read_b128 v[210:213], v201 offset:7168
	global_load_lds_dwordx4 v208, s[24:25]
	v_lshl_add_u64 v[202:203], s[24:25], 0, v[206:207]
	s_add_i32 m0, s39, 0xe000
	s_nop 0
	global_load_lds_dwordx4 v206, s[24:25]
	s_waitcnt vmcnt(8)
	s_waitcnt lgkmcnt(0)
	s_barrier
	s_setprio 1
	s_waitcnt lgkmcnt(0)
	v_mfma_f32_16x16x32_bf16 v[170:173], v[70:73], v[158:161], v[170:173]
	v_mfma_f32_16x16x32_bf16 v[170:173], v[74:77], v[162:165], v[170:173]
	v_mfma_f32_16x16x32_bf16 v[166:169], v[86:89], v[158:161], v[166:169]
	v_mfma_f32_16x16x32_bf16 v[166:169], v[98:101], v[162:165], v[166:169]
	v_mfma_f32_16x16x32_bf16 v[142:145], v[70:73], v[174:177], v[142:145]
	v_mfma_f32_16x16x32_bf16 v[142:145], v[74:77], v[178:181], v[142:145]
	v_mfma_f32_16x16x32_bf16 v[138:141], v[86:89], v[174:177], v[138:141]
	v_mfma_f32_16x16x32_bf16 v[138:141], v[98:101], v[178:181], v[138:141]
	v_mfma_f32_16x16x32_bf16 v[118:121], v[70:73], v[182:185], v[118:121]
	v_mfma_f32_16x16x32_bf16 v[118:121], v[74:77], v[186:189], v[118:121]
	v_mfma_f32_16x16x32_bf16 v[114:117], v[86:89], v[182:185], v[114:117]
	v_mfma_f32_16x16x32_bf16 v[114:117], v[98:101], v[186:189], v[114:117]
	v_mfma_f32_16x16x32_bf16 v[94:97], v[70:73], v[190:193], v[94:97]
	v_mfma_f32_16x16x32_bf16 v[94:97], v[74:77], v[210:213], v[94:97]
	v_mfma_f32_16x16x32_bf16 v[90:93], v[86:89], v[190:193], v[90:93]
	v_mfma_f32_16x16x32_bf16 v[90:93], v[98:101], v[210:213], v[90:93]
	s_setprio 0
	s_setprio 1
	v_mfma_f32_16x16x32_bf16 v[154:157], v[110:113], v[158:161], v[154:157]
	v_mfma_f32_16x16x32_bf16 v[154:157], v[122:125], v[162:165], v[154:157]
	v_mfma_f32_16x16x32_bf16 v[150:153], v[134:137], v[158:161], v[150:153]
	v_mfma_f32_16x16x32_bf16 v[150:153], v[146:149], v[162:165], v[150:153]
	v_mfma_f32_16x16x32_bf16 v[130:133], v[110:113], v[174:177], v[130:133]
	v_mfma_f32_16x16x32_bf16 v[130:133], v[122:125], v[178:181], v[130:133]
	v_mfma_f32_16x16x32_bf16 v[126:129], v[134:137], v[174:177], v[126:129]
	v_mfma_f32_16x16x32_bf16 v[126:129], v[146:149], v[178:181], v[126:129]
	v_mfma_f32_16x16x32_bf16 v[106:109], v[110:113], v[182:185], v[106:109]
	v_mfma_f32_16x16x32_bf16 v[106:109], v[122:125], v[186:189], v[106:109]
	v_mfma_f32_16x16x32_bf16 v[102:105], v[134:137], v[182:185], v[102:105]
	v_mfma_f32_16x16x32_bf16 v[102:105], v[146:149], v[186:189], v[102:105]
	v_mfma_f32_16x16x32_bf16 v[82:85], v[110:113], v[190:193], v[82:85]
	v_mfma_f32_16x16x32_bf16 v[82:85], v[122:125], v[210:213], v[82:85]
	v_mfma_f32_16x16x32_bf16 v[78:81], v[134:137], v[190:193], v[78:81]
	v_mfma_f32_16x16x32_bf16 v[78:81], v[146:149], v[210:213], v[78:81]
	s_setprio 0
	s_barrier
	s_add_i32 s24, s33, s38
	v_lshl_add_u64 v[202:203], s[26:27], 0, v[0:1]
	s_mov_b32 m0, s24
	ds_read_b128 v[158:161], v201 offset:16384
	ds_read_b128 v[162:165], v201 offset:17408
	ds_read_b128 v[174:177], v201 offset:18432
	ds_read_b128 v[178:181], v201 offset:19456
	ds_read_b128 v[182:185], v201 offset:20480
	ds_read_b128 v[186:189], v201 offset:21504
	ds_read_b128 v[190:193], v201 offset:22528
	ds_read_b128 v[210:213], v201 offset:23552
	global_load_lds_dwordx4 v0, s[26:27]
	s_add_i32 m0, s24, 0x2000
	s_add_u32 s24, s26, 0x160000
	v_lshl_add_u64 v[214:215], s[26:27], 0, v[196:197]
	s_addc_u32 s25, s27, 0
	s_add_i32 s33, s54, s38
	global_load_lds_dwordx4 v196, s[26:27]
	v_lshl_add_u64 v[216:217], s[24:25], 0, v[0:1]
	s_mov_b32 m0, s33
	v_lshl_add_u64 v[218:219], s[28:29], 0, v[194:195]
	global_load_lds_dwordx4 v0, s[24:25]
	v_lshl_add_u64 v[216:217], s[24:25], 0, v[196:197]
	s_add_i32 m0, s33, 0x2000
	s_nop 0
	global_load_lds_dwordx4 v196, s[24:25]
	v_lshl_add_u64 v[216:217], s[28:29], 0, v[14:15]
	s_mov_b32 m0, s39
	s_nop 0
	global_load_lds_dwordx4 v14, s[28:29]
	s_mov_b32 m0, s40
	s_nop 0
	global_load_lds_dwordx4 v194, s[28:29]
	s_waitcnt vmcnt(8)
	s_waitcnt lgkmcnt(0)
	s_barrier
; #define PG8_STAGE(bufoff, gbase, voff) do { _Pragma("unroll") for (int _i = 0; _i < 2; ++_i) \
;         __builtin_amdgcn_global_load_lds((const unsigned*)((const char*)(gbase) + (voff)[_i]), (PG8_LAS unsigned*)(lds + (bufoff) + ldsw + _i * 8192), 16, 0, 0); } while (0)
; #define PG8_LDA(dst, b, h) do { _Pragma("unroll") for (int m = 0; m < 4; ++m) _Pragma("unroll") for (int k = 0; k < 2; ++k) dst[m][k] = *(const PG8_LAS bf16x8*)(lds + PG8_SA(b, h) + aoff + m * 2048 + k * 1024); } while (0)
; #define PG8_LDB(dst, b, h) do { _Pragma("unroll") for (int n = 0; n < 2; ++n) _Pragma("unroll") for (int k = 0; k < 2; ++k) dst[n][k] = *(const PG8_LAS bf16x8*)(lds + PG8_SB(b, h) + boff + n * 2048 + k * 1024); } while (0)
; #define PG8_MMA(ai, bj, At, Bt) do { __builtin_amdgcn_s_setprio(1); _Pragma("unroll") for (int m = 0; m < 4; ++m) _Pragma("unroll") for (int n = 0; n < 2; ++n) _Pragma("unroll") for (int k = 0; k < 2; ++k) \
;         acc[ai][bj][m][n] = __builtin_amdgcn_mfma_f32_16x16x32_bf16(Bt[n][k], At[m][k], acc[ai][bj][m][n], 0, 0, 0); __builtin_amdgcn_s_setprio(0); } while (0)
; #define PG8_WAIT_V(n) asm volatile("s_waitcnt vmcnt(" #n ")" ::: "memory")
; #define PG8_WAIT_L(n) asm volatile("s_waitcnt lgkmcnt(" #n ")" ::: "memory")
; #define PG8_BAR __builtin_amdgcn_s_barrier()
; #define PG8_SCHED __builtin_amdgcn_sched_barrier(0)
; template <class Epi, class Sched, bool ALIGN_EPI = false, bool SP2 = false>
; __device__ __forceinline__ void gemm_phase(PG8_LAS unsigned char* lds, const Gemm g, const Sched& S, const Epi& E) {
;     ...
;             PG8_WAIT_V(8); PG8_WAIT_L(0); PG8_BAR; PG8_MMA(1, 0, At, B0); PG8_MMA(1, 1, At, B1); PG8_BAR; PG8_SCHED;
;             PG8_LDB(B0, 1, 0); PG8_LDB(B1, 1, 1); PG8_SCHED; PG8_LDA(At, 1, 0); PG8_STAGE(PG8_SA(0, 1), a2 + hstep, voffA);
;             PG8_WAIT_V(8); PG8_WAIT_L(0); PG8_BAR; PG8_MMA(0, 0, At, B0); PG8_MMA(0, 1, At, B1); PG8_BAR; PG8_SCHED;
	s_setprio 1
	s_waitcnt lgkmcnt(0)
	v_mfma_f32_16x16x32_bf16 v[66:69], v[70:73], v[158:161], v[66:69]
	v_mfma_f32_16x16x32_bf16 v[66:69], v[74:77], v[162:165], v[66:69]
	v_mfma_f32_16x16x32_bf16 v[62:65], v[86:89], v[158:161], v[62:65]
	v_mfma_f32_16x16x32_bf16 v[62:65], v[98:101], v[162:165], v[62:65]
	v_mfma_f32_16x16x32_bf16 v[50:53], v[70:73], v[174:177], v[50:53]
	v_mfma_f32_16x16x32_bf16 v[50:53], v[74:77], v[178:181], v[50:53]
	v_mfma_f32_16x16x32_bf16 v[46:49], v[86:89], v[174:177], v[46:49]
	v_mfma_f32_16x16x32_bf16 v[46:49], v[98:101], v[178:181], v[46:49]
	v_mfma_f32_16x16x32_bf16 v[34:37], v[70:73], v[182:185], v[34:37]
	v_mfma_f32_16x16x32_bf16 v[34:37], v[74:77], v[186:189], v[34:37]
	v_mfma_f32_16x16x32_bf16 v[30:33], v[86:89], v[182:185], v[30:33]
	v_mfma_f32_16x16x32_bf16 v[30:33], v[98:101], v[186:189], v[30:33]
	v_mfma_f32_16x16x32_bf16 v[18:21], v[70:73], v[190:193], v[18:21]
	v_mfma_f32_16x16x32_bf16 v[18:21], v[74:77], v[210:213], v[18:21]
	v_mfma_f32_16x16x32_bf16 v[10:13], v[86:89], v[190:193], v[10:13]
	v_mfma_f32_16x16x32_bf16 v[10:13], v[98:101], v[210:213], v[10:13]
	s_setprio 0
	s_setprio 1
	v_mfma_f32_16x16x32_bf16 v[58:61], v[110:113], v[158:161], v[58:61]
	v_mfma_f32_16x16x32_bf16 v[58:61], v[122:125], v[162:165], v[58:61]
	v_mfma_f32_16x16x32_bf16 v[54:57], v[134:137], v[158:161], v[54:57]
	v_mfma_f32_16x16x32_bf16 v[54:57], v[146:149], v[162:165], v[54:57]
	v_mfma_f32_16x16x32_bf16 v[42:45], v[110:113], v[174:177], v[42:45]
	v_mfma_f32_16x16x32_bf16 v[42:45], v[122:125], v[178:181], v[42:45]
	v_mfma_f32_16x16x32_bf16 v[38:41], v[134:137], v[174:177], v[38:41]
	v_mfma_f32_16x16x32_bf16 v[38:41], v[146:149], v[178:181], v[38:41]
	v_mfma_f32_16x16x32_bf16 v[26:29], v[110:113], v[182:185], v[26:29]
	v_mfma_f32_16x16x32_bf16 v[26:29], v[122:125], v[186:189], v[26:29]
	v_mfma_f32_16x16x32_bf16 v[22:25], v[134:137], v[182:185], v[22:25]
	v_mfma_f32_16x16x32_bf16 v[22:25], v[146:149], v[186:189], v[22:25]
	v_mfma_f32_16x16x32_bf16 v[6:9], v[110:113], v[190:193], v[6:9]
	v_mfma_f32_16x16x32_bf16 v[6:9], v[122:125], v[210:213], v[6:9]
	v_mfma_f32_16x16x32_bf16 v[2:5], v[134:137], v[190:193], v[2:5]
	v_mfma_f32_16x16x32_bf16 v[2:5], v[146:149], v[210:213], v[2:5]
	s_setprio 0
	s_barrier
	s_add_i32 s33, 0, 0x18000
	s_add_i32 s54, 0, 0x1c000
	v_add_u32_e32 v98, s33, v199
	v_add_u32_e32 v146, s54, v199
	ds_read_b128 v[70:73], v98
	ds_read_b128 v[74:77], v98 offset:1024
	ds_read_b128 v[86:89], v98 offset:2048
	ds_read_b128 v[98:101], v98 offset:3072
	ds_read_b128 v[110:113], v146
	ds_read_b128 v[122:125], v146 offset:1024
	ds_read_b128 v[134:137], v146 offset:2048
	ds_read_b128 v[146:149], v146 offset:3072
	s_add_u32 s24, s28, 0x160000
	s_addc_u32 s25, s29, 0
	s_mov_b32 m0, s41
	v_lshl_add_u64 v[220:221], s[24:25], 0, v[14:15]
	ds_read_b128 v[158:161], v201 offset:32768
	ds_read_b128 v[162:165], v201 offset:33792
	ds_read_b128 v[174:177], v201 offset:34816
	ds_read_b128 v[178:181], v201 offset:35840
	ds_read_b128 v[182:185], v201 offset:36864
	ds_read_b128 v[186:189], v201 offset:37888
	ds_read_b128 v[190:193], v201 offset:38912
	ds_read_b128 v[210:213], v201 offset:39936
	global_load_lds_dwordx4 v14, s[24:25]
	v_lshl_add_u64 v[220:221], s[24:25], 0, v[194:195]
	s_mov_b32 m0, s42
	s_nop 0
	global_load_lds_dwordx4 v194, s[24:25]
	s_waitcnt vmcnt(8)
	s_waitcnt lgkmcnt(0)
	s_barrier
	s_setprio 1
	s_waitcnt lgkmcnt(0)
	v_mfma_f32_16x16x32_bf16 v[170:173], v[70:73], v[158:161], v[170:173]
	v_mfma_f32_16x16x32_bf16 v[170:173], v[74:77], v[162:165], v[170:173]
	v_mfma_f32_16x16x32_bf16 v[166:169], v[86:89], v[158:161], v[166:169]
	v_mfma_f32_16x16x32_bf16 v[166:169], v[98:101], v[162:165], v[166:169]
	v_mfma_f32_16x16x32_bf16 v[142:145], v[70:73], v[174:177], v[142:145]
	v_mfma_f32_16x16x32_bf16 v[142:145], v[74:77], v[178:181], v[142:145]
	v_mfma_f32_16x16x32_bf16 v[138:141], v[86:89], v[174:177], v[138:141]
	v_mfma_f32_16x16x32_bf16 v[138:141], v[98:101], v[178:181], v[138:141]
	v_mfma_f32_16x16x32_bf16 v[118:121], v[70:73], v[182:185], v[118:121]
	v_mfma_f32_16x16x32_bf16 v[118:121], v[74:77], v[186:189], v[118:121]
	v_mfma_f32_16x16x32_bf16 v[114:117], v[86:89], v[182:185], v[114:117]
	v_mfma_f32_16x16x32_bf16 v[114:117], v[98:101], v[186:189], v[114:117]
	v_mfma_f32_16x16x32_bf16 v[94:97], v[70:73], v[190:193], v[94:97]
	v_mfma_f32_16x16x32_bf16 v[94:97], v[74:77], v[210:213], v[94:97]
	v_mfma_f32_16x16x32_bf16 v[90:93], v[86:89], v[190:193], v[90:93]
	v_mfma_f32_16x16x32_bf16 v[90:93], v[98:101], v[210:213], v[90:93]
	s_setprio 0
	s_setprio 1
	v_mfma_f32_16x16x32_bf16 v[154:157], v[110:113], v[158:161], v[154:157]
	v_mfma_f32_16x16x32_bf16 v[154:157], v[122:125], v[162:165], v[154:157]
	v_mfma_f32_16x16x32_bf16 v[150:153], v[134:137], v[158:161], v[150:153]
	v_mfma_f32_16x16x32_bf16 v[150:153], v[146:149], v[162:165], v[150:153]
	v_mfma_f32_16x16x32_bf16 v[130:133], v[110:113], v[174:177], v[130:133]
	v_mfma_f32_16x16x32_bf16 v[130:133], v[122:125], v[178:181], v[130:133]
	v_mfma_f32_16x16x32_bf16 v[126:129], v[134:137], v[174:177], v[126:129]
	v_mfma_f32_16x16x32_bf16 v[126:129], v[146:149], v[178:181], v[126:129]
	v_mfma_f32_16x16x32_bf16 v[106:109], v[110:113], v[182:185], v[106:109]
	v_mfma_f32_16x16x32_bf16 v[106:109], v[122:125], v[186:189], v[106:109]
	v_mfma_f32_16x16x32_bf16 v[102:105], v[134:137], v[182:185], v[102:105]
	v_mfma_f32_16x16x32_bf16 v[102:105], v[146:149], v[186:189], v[102:105]
	v_mfma_f32_16x16x32_bf16 v[82:85], v[110:113], v[190:193], v[82:85]
	v_mfma_f32_16x16x32_bf16 v[82:85], v[122:125], v[210:213], v[82:85]
	v_mfma_f32_16x16x32_bf16 v[78:81], v[134:137], v[190:193], v[78:81]
	v_mfma_f32_16x16x32_bf16 v[78:81], v[146:149], v[210:213], v[78:81]
	s_setprio 0
	s_barrier
; #define PG8_STAGE(bufoff, gbase, voff) do { _Pragma("unroll") for (int _i = 0; _i < 2; ++_i) \
;         __builtin_amdgcn_global_load_lds((const unsigned*)((const char*)(gbase) + (voff)[_i]), (PG8_LAS unsigned*)(lds + (bufoff) + ldsw + _i * 8192), 16, 0, 0); } while (0)
; #define PG8_LDA(dst, b, h) do { _Pragma("unroll") for (int m = 0; m < 4; ++m) _Pragma("unroll") for (int k = 0; k < 2; ++k) dst[m][k] = *(const PG8_LAS bf16x8*)(lds + PG8_SA(b, h) + aoff + m * 2048 + k * 1024); } while (0)
; #define PG8_MMA(ai, bj, At, Bt) do { __builtin_amdgcn_s_setprio(1); _Pragma("unroll") for (int m = 0; m < 4; ++m) _Pragma("unroll") for (int n = 0; n < 2; ++n) _Pragma("unroll") for (int k = 0; k < 2; ++k) \
;         acc[ai][bj][m][n] = __builtin_amdgcn_mfma_f32_16x16x32_bf16(Bt[n][k], At[m][k], acc[ai][bj][m][n], 0, 0, 0); __builtin_amdgcn_s_setprio(0); } while (0)
; #define PG8_WAIT_V(n) asm volatile("s_waitcnt vmcnt(" #n ")" ::: "memory")
; #define PG8_WAIT_L(n) asm volatile("s_waitcnt lgkmcnt(" #n ")" ::: "memory")
; #define PG8_BAR __builtin_amdgcn_s_barrier()
; #define PG8_SCHED __builtin_amdgcn_sched_barrier(0)
; template <class Epi, class Sched, bool ALIGN_EPI = false, bool SP2 = false>
; __device__ __forceinline__ void gemm_phase(PG8_LAS unsigned char* lds, const Gemm g, const Sched& S, const Epi& E) {
;     ...
;             PG8_LDA(At, 1, 1); PG8_STAGE(PG8_SB(1, 0), b3, voffB); PG8_STAGE(PG8_SB(1, 1), b3 + hstep, voffB); PG8_STAGE(PG8_SA(1, 0), a3, voffA);
;             PG8_WAIT_V(8); PG8_WAIT_L(0); PG8_BAR; PG8_MMA(1, 0, At, B0); PG8_MMA(1, 1, At, B1); PG8_BAR; PG8_SCHED;
	s_add_i32 s24, s33, s38
	v_lshl_add_u64 v[202:203], v[202:203], 0, s[92:93]
	s_mov_b32 m0, s24
	ds_read_b128 v[158:161], v201 offset:49152
	ds_read_b128 v[162:165], v201 offset:50176
	ds_read_b128 v[174:177], v201 offset:51200
	ds_read_b128 v[178:181], v201 offset:52224
	ds_read_b128 v[182:185], v201 offset:53248
	ds_read_b128 v[186:189], v201 offset:54272
	ds_read_b128 v[190:193], v201 offset:55296
	ds_read_b128 v[210:213], v201 offset:56320
	global_load_lds_dwordx4 v[202:203], off
	s_add_i32 m0, s24, 0x2000
	s_add_u32 s24, s26, 0x160080
	v_lshl_add_u64 v[202:203], v[214:215], 0, s[92:93]
	s_addc_u32 s25, s27, 0
	s_add_i32 s26, s54, s38
	global_load_lds_dwordx4 v[202:203], off
	v_lshl_add_u64 v[202:203], s[24:25], 0, v[0:1]
	s_mov_b32 m0, s26
	s_nop 0
	global_load_lds_dwordx4 v0, s[24:25]
	v_lshl_add_u64 v[202:203], s[24:25], 0, v[196:197]
	s_add_i32 m0, s26, 0x2000
	s_nop 0
	global_load_lds_dwordx4 v196, s[24:25]
	v_lshl_add_u64 v[202:203], v[216:217], 0, s[92:93]
	s_mov_b32 m0, s44
	s_nop 0
	global_load_lds_dwordx4 v[202:203], off
	v_lshl_add_u64 v[202:203], v[218:219], 0, s[92:93]
	s_mov_b32 m0, s45
	s_nop 0
	global_load_lds_dwordx4 v[202:203], off
	s_waitcnt vmcnt(8)
	s_waitcnt lgkmcnt(0)
	s_barrier
	s_setprio 1
	s_waitcnt lgkmcnt(0)
	v_mfma_f32_16x16x32_bf16 v[66:69], v[70:73], v[158:161], v[66:69]
	v_mfma_f32_16x16x32_bf16 v[66:69], v[74:77], v[162:165], v[66:69]
	v_mfma_f32_16x16x32_bf16 v[62:65], v[86:89], v[158:161], v[62:65]
	v_mfma_f32_16x16x32_bf16 v[62:65], v[98:101], v[162:165], v[62:65]
	v_mfma_f32_16x16x32_bf16 v[50:53], v[70:73], v[174:177], v[50:53]
	v_mfma_f32_16x16x32_bf16 v[50:53], v[74:77], v[178:181], v[50:53]
	v_mfma_f32_16x16x32_bf16 v[46:49], v[86:89], v[174:177], v[46:49]
	v_mfma_f32_16x16x32_bf16 v[46:49], v[98:101], v[178:181], v[46:49]
	v_mfma_f32_16x16x32_bf16 v[34:37], v[70:73], v[182:185], v[34:37]
	v_mfma_f32_16x16x32_bf16 v[34:37], v[74:77], v[186:189], v[34:37]
	v_mfma_f32_16x16x32_bf16 v[30:33], v[86:89], v[182:185], v[30:33]
	v_mfma_f32_16x16x32_bf16 v[30:33], v[98:101], v[186:189], v[30:33]
	v_mfma_f32_16x16x32_bf16 v[18:21], v[70:73], v[190:193], v[18:21]
	v_mfma_f32_16x16x32_bf16 v[18:21], v[74:77], v[210:213], v[18:21]
	v_mfma_f32_16x16x32_bf16 v[10:13], v[86:89], v[190:193], v[10:13]
	v_mfma_f32_16x16x32_bf16 v[10:13], v[98:101], v[210:213], v[10:13]
	s_setprio 0
	s_setprio 1
	v_mfma_f32_16x16x32_bf16 v[58:61], v[110:113], v[158:161], v[58:61]
	v_mfma_f32_16x16x32_bf16 v[58:61], v[122:125], v[162:165], v[58:61]
	v_mfma_f32_16x16x32_bf16 v[54:57], v[134:137], v[158:161], v[54:57]
	v_mfma_f32_16x16x32_bf16 v[54:57], v[146:149], v[162:165], v[54:57]
	v_mfma_f32_16x16x32_bf16 v[42:45], v[110:113], v[174:177], v[42:45]
	v_mfma_f32_16x16x32_bf16 v[42:45], v[122:125], v[178:181], v[42:45]
	v_mfma_f32_16x16x32_bf16 v[38:41], v[134:137], v[174:177], v[38:41]
	v_mfma_f32_16x16x32_bf16 v[38:41], v[146:149], v[178:181], v[38:41]
	v_mfma_f32_16x16x32_bf16 v[26:29], v[110:113], v[182:185], v[26:29]
	v_mfma_f32_16x16x32_bf16 v[26:29], v[122:125], v[186:189], v[26:29]
	v_mfma_f32_16x16x32_bf16 v[22:25], v[134:137], v[182:185], v[22:25]
	v_mfma_f32_16x16x32_bf16 v[22:25], v[146:149], v[186:189], v[22:25]
	v_mfma_f32_16x16x32_bf16 v[6:9], v[110:113], v[190:193], v[6:9]
	v_mfma_f32_16x16x32_bf16 v[6:9], v[122:125], v[210:213], v[6:9]
	v_mfma_f32_16x16x32_bf16 v[2:5], v[134:137], v[190:193], v[2:5]
	v_mfma_f32_16x16x32_bf16 v[2:5], v[146:149], v[210:213], v[2:5]
	s_setprio 0
	s_barrier
	s_add_i32 s53, s53, 2
	s_add_u32 s51, s51, 0x100
	s_addc_u32 s52, s52, 0
	s_cmpk_gt_u32 s53, 0x55
	s_mov_b64 s[24:25], s[4:5]
	s_cbranch_scc0 .LBB0_1329
	s_and_b64 vcc, exec, s[16:17]
	s_cbranch_vccz .LBB0_1332
	s_barrier
